# v16 plus address arithmetic (SALU and 64-bit VALU adds) of loader segments 1-3 moved into the same wave's preceding MFMA block in 9 GEMM K loops, reused address pairs renamed to free VGPR pairs
# speedup vs baseline: 1.0020x; 1.0020x over previous
.Lsp_skip0:
.LBB0_233:
	ds_read_b128 v[162:165], v155
	ds_read_b128 v[166:169], v155 offset:1024
	ds_read_b128 v[170:173], v155 offset:2048
	ds_read_b128 v[174:177], v155 offset:3072
	ds_read_b128 v[178:181], v158
	ds_read_b128 v[182:185], v158 offset:1024
	ds_read_b128 v[186:189], v158 offset:2048
	ds_read_b128 v[190:193], v158 offset:3072
	ds_read_b128 v[194:197], v159
	ds_read_b128 v[198:201], v159 offset:1024
	ds_read_b128 v[202:205], v159 offset:2048
	ds_read_b128 v[206:209], v159 offset:3072
	ds_read_b128 v[210:213], v159 offset:4096
	ds_read_b128 v[214:217], v159 offset:5120
	ds_read_b128 v[218:221], v159 offset:6144
	ds_read_b128 v[222:225], v159 offset:7168
	s_add_u32 s36, s34, 0xfff00080
	s_addc_u32 s37, s35, -1
	s_cmp_eq_u32 s68, 60
	s_cselect_b32 s39, s25, s37
	s_cselect_b32 s38, s64, s36
	s_cselect_b32 s37, s23, s67
	s_cselect_b32 s36, s65, s66
	v_lshl_add_u64 v[144:145], s[34:35], 0, v[138:139]
	s_add_i32 m0, s31, 0xc000
	s_nop 0
	global_load_lds_dwordx4 v[144:145], off
	v_lshl_add_u64 v[144:145], s[34:35], 0, v[136:137]
	s_add_i32 m0, s31, 0xe000
	s_nop 0
	global_load_lds_dwordx4 v[144:145], off
	s_waitcnt vmcnt(8)
	s_waitcnt lgkmcnt(0)
	s_barrier
	s_waitcnt lgkmcnt(0)
	v_mfma_f32_16x16x32_bf16 v[124:127], v[162:165], v[194:197], v[124:127]
	v_mfma_f32_16x16x32_bf16 v[120:123], v[170:173], v[194:197], v[120:123]
	v_mfma_f32_16x16x32_bf16 v[108:111], v[162:165], v[202:205], v[108:111]
	v_mfma_f32_16x16x32_bf16 v[104:107], v[170:173], v[202:205], v[104:107]
	s_add_i32 s69, s57, s40
	v_mfma_f32_16x16x32_bf16 v[92:95], v[162:165], v[210:213], v[92:95]
	v_mfma_f32_16x16x32_bf16 v[88:91], v[170:173], v[210:213], v[88:91]
	v_lshl_add_u64 v[144:145], s[36:37], 0, v[130:131]
	v_mfma_f32_16x16x32_bf16 v[76:79], v[162:165], v[218:221], v[76:79]
	v_mfma_f32_16x16x32_bf16 v[72:75], v[170:173], v[218:221], v[72:75]
	s_add_u32 s70, s36, 0x100000
	v_mfma_f32_16x16x32_bf16 v[124:127], v[166:169], v[198:201], v[124:127]
	v_mfma_f32_16x16x32_bf16 v[120:123], v[174:177], v[198:201], v[120:123]
	v_lshl_add_u64 v[150:151], s[36:37], 0, v[134:135]
	v_mfma_f32_16x16x32_bf16 v[108:111], v[166:169], v[206:209], v[108:111]
	v_mfma_f32_16x16x32_bf16 v[104:107], v[174:177], v[206:209], v[104:107]
	s_addc_u32 s71, s37, 0
	v_mfma_f32_16x16x32_bf16 v[92:95], v[166:169], v[214:217], v[92:95]
	v_mfma_f32_16x16x32_bf16 v[88:91], v[174:177], v[214:217], v[88:91]
	v_lshl_add_u64 v[248:249], s[70:71], 0, v[130:131]
	v_mfma_f32_16x16x32_bf16 v[76:79], v[166:169], v[222:225], v[76:79]
	v_mfma_f32_16x16x32_bf16 v[72:75], v[174:177], v[222:225], v[72:75]
	v_lshl_add_u64 v[226:227], s[38:39], 0, v[132:133]
	v_mfma_f32_16x16x32_bf16 v[116:119], v[178:181], v[194:197], v[116:119]
	v_mfma_f32_16x16x32_bf16 v[112:115], v[186:189], v[194:197], v[112:115]
	v_lshl_add_u64 v[250:251], s[70:71], 0, v[134:135]
	v_mfma_f32_16x16x32_bf16 v[100:103], v[178:181], v[202:205], v[100:103]
	v_mfma_f32_16x16x32_bf16 v[96:99], v[186:189], v[202:205], v[96:99]
	v_lshl_add_u64 v[156:157], s[38:39], 0, v[128:129]
	v_mfma_f32_16x16x32_bf16 v[84:87], v[178:181], v[210:213], v[84:87]
	v_mfma_f32_16x16x32_bf16 v[80:83], v[186:189], v[210:213], v[80:83]
	v_mfma_f32_16x16x32_bf16 v[68:71], v[178:181], v[218:221], v[68:71]
	v_mfma_f32_16x16x32_bf16 v[64:67], v[186:189], v[218:221], v[64:67]
	v_mfma_f32_16x16x32_bf16 v[116:119], v[182:185], v[198:201], v[116:119]
	v_mfma_f32_16x16x32_bf16 v[112:115], v[190:193], v[198:201], v[112:115]
	v_mfma_f32_16x16x32_bf16 v[100:103], v[182:185], v[206:209], v[100:103]
	v_mfma_f32_16x16x32_bf16 v[96:99], v[190:193], v[206:209], v[96:99]
	v_mfma_f32_16x16x32_bf16 v[84:87], v[182:185], v[214:217], v[84:87]
	v_mfma_f32_16x16x32_bf16 v[80:83], v[190:193], v[214:217], v[80:83]
	v_mfma_f32_16x16x32_bf16 v[68:71], v[182:185], v[222:225], v[68:71]
	v_mfma_f32_16x16x32_bf16 v[64:67], v[190:193], v[222:225], v[64:67]
	s_barrier
	ds_read_b128 v[194:197], v159 offset:16384
	ds_read_b128 v[198:201], v159 offset:17408
	ds_read_b128 v[202:205], v159 offset:18432
	ds_read_b128 v[206:209], v159 offset:19456
	ds_read_b128 v[210:213], v159 offset:20480
	ds_read_b128 v[214:217], v159 offset:21504
	ds_read_b128 v[218:221], v159 offset:22528
	ds_read_b128 v[222:225], v159 offset:23552
	s_mov_b32 m0, s69
	s_nop 0
	global_load_lds_dwordx4 v[144:145], off
	s_add_i32 m0, s69, 0x2000
	s_add_i32 s69, s58, s40
	global_load_lds_dwordx4 v[150:151], off
	s_mov_b32 m0, s69
	s_nop 0
	global_load_lds_dwordx4 v[248:249], off
	s_add_i32 m0, s69, 0x2000
	s_nop 0
	global_load_lds_dwordx4 v[250:251], off
	s_mov_b32 m0, s31
	s_nop 0
	global_load_lds_dwordx4 v[156:157], off
	s_mov_b32 m0, s50
	s_nop 0
	global_load_lds_dwordx4 v[226:227], off
	s_waitcnt vmcnt(8)
	s_waitcnt lgkmcnt(0)
	s_barrier
	s_waitcnt lgkmcnt(0)
	v_mfma_f32_16x16x32_bf16 v[60:63], v[162:165], v[194:197], v[60:63]
	v_mfma_f32_16x16x32_bf16 v[56:59], v[170:173], v[194:197], v[56:59]
	v_mfma_f32_16x16x32_bf16 v[48:51], v[162:165], v[202:205], v[48:51]
	v_mfma_f32_16x16x32_bf16 v[40:43], v[170:173], v[202:205], v[40:43]
	s_add_i32 s69, 0, 0x18000
	v_mfma_f32_16x16x32_bf16 v[32:35], v[162:165], v[210:213], v[32:35]
	v_mfma_f32_16x16x32_bf16 v[24:27], v[170:173], v[210:213], v[24:27]
	v_add_u32_e32 v146, s69, v149
	v_mfma_f32_16x16x32_bf16 v[16:19], v[162:165], v[218:221], v[16:19]
	v_mfma_f32_16x16x32_bf16 v[8:11], v[170:173], v[218:221], v[8:11]
	s_add_i32 s70, 0, 0x1c000
	v_mfma_f32_16x16x32_bf16 v[60:63], v[166:169], v[198:201], v[60:63]
	v_mfma_f32_16x16x32_bf16 v[56:59], v[174:177], v[198:201], v[56:59]
	s_add_u32 s38, s38, 0x100000
	v_mfma_f32_16x16x32_bf16 v[48:51], v[166:169], v[206:209], v[48:51]
	v_mfma_f32_16x16x32_bf16 v[40:43], v[174:177], v[206:209], v[40:43]
	s_addc_u32 s39, s39, 0
	v_mfma_f32_16x16x32_bf16 v[32:35], v[166:169], v[214:217], v[32:35]
	v_mfma_f32_16x16x32_bf16 v[24:27], v[174:177], v[214:217], v[24:27]
	v_lshl_add_u64 v[248:249], s[38:39], 0, v[128:129]
	v_mfma_f32_16x16x32_bf16 v[16:19], v[166:169], v[222:225], v[16:19]
	v_mfma_f32_16x16x32_bf16 v[8:11], v[174:177], v[222:225], v[8:11]
	v_lshl_add_u64 v[228:229], s[38:39], 0, v[132:133]
	v_mfma_f32_16x16x32_bf16 v[52:55], v[178:181], v[194:197], v[52:55]
	v_mfma_f32_16x16x32_bf16 v[44:47], v[186:189], v[194:197], v[44:47]
	v_mfma_f32_16x16x32_bf16 v[36:39], v[178:181], v[202:205], v[36:39]
	v_mfma_f32_16x16x32_bf16 v[28:31], v[186:189], v[202:205], v[28:31]
	v_mfma_f32_16x16x32_bf16 v[20:23], v[178:181], v[210:213], v[20:23]
	v_mfma_f32_16x16x32_bf16 v[12:15], v[186:189], v[210:213], v[12:15]
	v_mfma_f32_16x16x32_bf16 v[4:7], v[178:181], v[218:221], v[4:7]
	v_mfma_f32_16x16x32_bf16 v[0:3], v[186:189], v[218:221], v[0:3]
	v_mfma_f32_16x16x32_bf16 v[52:55], v[182:185], v[198:201], v[52:55]
	v_mfma_f32_16x16x32_bf16 v[44:47], v[190:193], v[198:201], v[44:47]
	v_mfma_f32_16x16x32_bf16 v[36:39], v[182:185], v[206:209], v[36:39]
	v_mfma_f32_16x16x32_bf16 v[28:31], v[190:193], v[206:209], v[28:31]
	v_mfma_f32_16x16x32_bf16 v[20:23], v[182:185], v[214:217], v[20:23]
	v_mfma_f32_16x16x32_bf16 v[12:15], v[190:193], v[214:217], v[12:15]
	v_mfma_f32_16x16x32_bf16 v[4:7], v[182:185], v[222:225], v[4:7]
	v_mfma_f32_16x16x32_bf16 v[0:3], v[190:193], v[222:225], v[0:3]
	s_barrier
	ds_read_b128 v[194:197], v159 offset:32768
	ds_read_b128 v[198:201], v159 offset:33792
	ds_read_b128 v[202:205], v159 offset:34816
	ds_read_b128 v[206:209], v159 offset:35840
	ds_read_b128 v[210:213], v159 offset:36864
	ds_read_b128 v[214:217], v159 offset:37888
	ds_read_b128 v[218:221], v159 offset:38912
	ds_read_b128 v[222:225], v159 offset:39936
	ds_read_b128 v[162:165], v146
	ds_read_b128 v[166:169], v146 offset:1024
	ds_read_b128 v[170:173], v146 offset:2048
	ds_read_b128 v[174:177], v146 offset:3072
	v_add_u32_e32 v146, s70, v149
	ds_read_b128 v[178:181], v146
	ds_read_b128 v[182:185], v146 offset:1024
	ds_read_b128 v[186:189], v146 offset:2048
	ds_read_b128 v[190:193], v146 offset:3072
	s_mov_b32 m0, s51
	s_nop 0
	global_load_lds_dwordx4 v[248:249], off
	s_mov_b32 m0, s52
	s_nop 0
	global_load_lds_dwordx4 v[228:229], off
	s_waitcnt vmcnt(8)
	s_waitcnt lgkmcnt(0)
	s_barrier
	s_waitcnt lgkmcnt(0)
	v_mfma_f32_16x16x32_bf16 v[124:127], v[162:165], v[194:197], v[124:127]
	v_mfma_f32_16x16x32_bf16 v[120:123], v[170:173], v[194:197], v[120:123]
	v_mfma_f32_16x16x32_bf16 v[108:111], v[162:165], v[202:205], v[108:111]
	v_mfma_f32_16x16x32_bf16 v[104:107], v[170:173], v[202:205], v[104:107]
	s_add_i32 s38, s69, s40
	v_mfma_f32_16x16x32_bf16 v[92:95], v[162:165], v[210:213], v[92:95]
	v_mfma_f32_16x16x32_bf16 v[88:91], v[170:173], v[210:213], v[88:91]
	v_lshl_add_u64 v[248:249], v[144:145], 0, s[12:13]
	v_mfma_f32_16x16x32_bf16 v[76:79], v[162:165], v[218:221], v[76:79]
	v_mfma_f32_16x16x32_bf16 v[72:75], v[170:173], v[218:221], v[72:75]
	s_add_u32 s36, s36, 0x100080
	v_mfma_f32_16x16x32_bf16 v[124:127], v[166:169], v[198:201], v[124:127]
	v_mfma_f32_16x16x32_bf16 v[120:123], v[174:177], v[198:201], v[120:123]
	v_lshl_add_u64 v[250:251], v[150:151], 0, s[12:13]
	v_mfma_f32_16x16x32_bf16 v[108:111], v[166:169], v[206:209], v[108:111]
	v_mfma_f32_16x16x32_bf16 v[104:107], v[174:177], v[206:209], v[104:107]
	s_addc_u32 s37, s37, 0
	v_mfma_f32_16x16x32_bf16 v[92:95], v[166:169], v[214:217], v[92:95]
	v_mfma_f32_16x16x32_bf16 v[88:91], v[174:177], v[214:217], v[88:91]
	v_lshl_add_u64 v[252:253], s[36:37], 0, v[130:131]
	v_mfma_f32_16x16x32_bf16 v[76:79], v[166:169], v[222:225], v[76:79]
	v_mfma_f32_16x16x32_bf16 v[72:75], v[174:177], v[222:225], v[72:75]
	v_lshl_add_u64 v[244:245], s[36:37], 0, v[134:135]
	v_mfma_f32_16x16x32_bf16 v[116:119], v[178:181], v[194:197], v[116:119]
	v_mfma_f32_16x16x32_bf16 v[112:115], v[186:189], v[194:197], v[112:115]
	v_lshl_add_u64 v[246:247], v[156:157], 0, s[12:13]
	v_mfma_f32_16x16x32_bf16 v[100:103], v[178:181], v[202:205], v[100:103]
	v_mfma_f32_16x16x32_bf16 v[96:99], v[186:189], v[202:205], v[96:99]
	v_lshl_add_u64 v[144:145], v[226:227], 0, s[12:13]
	v_mfma_f32_16x16x32_bf16 v[84:87], v[178:181], v[210:213], v[84:87]
	v_mfma_f32_16x16x32_bf16 v[80:83], v[186:189], v[210:213], v[80:83]
	v_mfma_f32_16x16x32_bf16 v[68:71], v[178:181], v[218:221], v[68:71]
	v_mfma_f32_16x16x32_bf16 v[64:67], v[186:189], v[218:221], v[64:67]
	v_mfma_f32_16x16x32_bf16 v[116:119], v[182:185], v[198:201], v[116:119]
	v_mfma_f32_16x16x32_bf16 v[112:115], v[190:193], v[198:201], v[112:115]
	v_mfma_f32_16x16x32_bf16 v[100:103], v[182:185], v[206:209], v[100:103]
	v_mfma_f32_16x16x32_bf16 v[96:99], v[190:193], v[206:209], v[96:99]
	v_mfma_f32_16x16x32_bf16 v[84:87], v[182:185], v[214:217], v[84:87]
	v_mfma_f32_16x16x32_bf16 v[80:83], v[190:193], v[214:217], v[80:83]
	v_mfma_f32_16x16x32_bf16 v[68:71], v[182:185], v[222:225], v[68:71]
	v_mfma_f32_16x16x32_bf16 v[64:67], v[190:193], v[222:225], v[64:67]
	s_barrier
	ds_read_b128 v[194:197], v159 offset:49152
	ds_read_b128 v[198:201], v159 offset:50176
	ds_read_b128 v[202:205], v159 offset:51200
	ds_read_b128 v[206:209], v159 offset:52224
	ds_read_b128 v[210:213], v159 offset:53248
	ds_read_b128 v[214:217], v159 offset:54272
	ds_read_b128 v[218:221], v159 offset:55296
	ds_read_b128 v[222:225], v159 offset:56320
	s_mov_b32 m0, s38
	s_nop 0
	global_load_lds_dwordx4 v[248:249], off
	s_add_i32 m0, s38, 0x2000
	s_add_i32 s38, s70, s40
	global_load_lds_dwordx4 v[250:251], off
	s_mov_b32 m0, s38
	s_nop 0
	global_load_lds_dwordx4 v[252:253], off
	s_add_i32 m0, s38, 0x2000
	s_nop 0
	global_load_lds_dwordx4 v[244:245], off
	s_mov_b32 m0, s54
	s_nop 0
	global_load_lds_dwordx4 v[246:247], off
	s_mov_b32 m0, s55
	s_nop 0
	global_load_lds_dwordx4 v[144:145], off
	s_waitcnt vmcnt(8)
	s_waitcnt lgkmcnt(0)
	s_barrier
	s_waitcnt lgkmcnt(0)
	v_mfma_f32_16x16x32_bf16 v[60:63], v[162:165], v[194:197], v[60:63]
	v_mfma_f32_16x16x32_bf16 v[56:59], v[170:173], v[194:197], v[56:59]
	v_mfma_f32_16x16x32_bf16 v[48:51], v[162:165], v[202:205], v[48:51]
	v_mfma_f32_16x16x32_bf16 v[40:43], v[170:173], v[202:205], v[40:43]
	v_mfma_f32_16x16x32_bf16 v[32:35], v[162:165], v[210:213], v[32:35]
	v_mfma_f32_16x16x32_bf16 v[24:27], v[170:173], v[210:213], v[24:27]
	v_mfma_f32_16x16x32_bf16 v[16:19], v[162:165], v[218:221], v[16:19]
	v_mfma_f32_16x16x32_bf16 v[8:11], v[170:173], v[218:221], v[8:11]
	v_mfma_f32_16x16x32_bf16 v[60:63], v[166:169], v[198:201], v[60:63]
	v_mfma_f32_16x16x32_bf16 v[56:59], v[174:177], v[198:201], v[56:59]
	v_mfma_f32_16x16x32_bf16 v[48:51], v[166:169], v[206:209], v[48:51]
	v_mfma_f32_16x16x32_bf16 v[40:43], v[174:177], v[206:209], v[40:43]
	v_mfma_f32_16x16x32_bf16 v[32:35], v[166:169], v[214:217], v[32:35]
	v_mfma_f32_16x16x32_bf16 v[24:27], v[174:177], v[214:217], v[24:27]
	v_mfma_f32_16x16x32_bf16 v[16:19], v[166:169], v[222:225], v[16:19]
	v_mfma_f32_16x16x32_bf16 v[8:11], v[174:177], v[222:225], v[8:11]
	v_mfma_f32_16x16x32_bf16 v[52:55], v[178:181], v[194:197], v[52:55]
	v_mfma_f32_16x16x32_bf16 v[44:47], v[186:189], v[194:197], v[44:47]
	v_mfma_f32_16x16x32_bf16 v[36:39], v[178:181], v[202:205], v[36:39]
	v_mfma_f32_16x16x32_bf16 v[28:31], v[186:189], v[202:205], v[28:31]
	v_mfma_f32_16x16x32_bf16 v[20:23], v[178:181], v[210:213], v[20:23]
	v_mfma_f32_16x16x32_bf16 v[12:15], v[186:189], v[210:213], v[12:15]
	v_mfma_f32_16x16x32_bf16 v[4:7], v[178:181], v[218:221], v[4:7]
	v_mfma_f32_16x16x32_bf16 v[0:3], v[186:189], v[218:221], v[0:3]
	v_mfma_f32_16x16x32_bf16 v[52:55], v[182:185], v[198:201], v[52:55]
	v_mfma_f32_16x16x32_bf16 v[44:47], v[190:193], v[198:201], v[44:47]
	v_mfma_f32_16x16x32_bf16 v[36:39], v[182:185], v[206:209], v[36:39]
	v_mfma_f32_16x16x32_bf16 v[28:31], v[190:193], v[206:209], v[28:31]
	v_mfma_f32_16x16x32_bf16 v[20:23], v[182:185], v[214:217], v[20:23]
	v_mfma_f32_16x16x32_bf16 v[12:15], v[190:193], v[214:217], v[12:15]
	v_mfma_f32_16x16x32_bf16 v[4:7], v[182:185], v[222:225], v[4:7]
	v_mfma_f32_16x16x32_bf16 v[0:3], v[190:193], v[222:225], v[0:3]
	s_barrier
	s_add_i32 s68, s68, 2
	s_add_u32 s66, s66, 0x100
	s_addc_u32 s67, s67, 0
	s_add_u32 s34, s34, 0x100
	s_addc_u32 s35, s35, 0
	s_cmp_gt_u32 s68, 61
	s_cbranch_scc0 .LBB0_233
	s_setprio 0
	s_and_b64 vcc, exec, s[14:15]
	s_cbranch_vccz .LBB0_236
	s_barrier

.Lsp_skip1:
.LBB0_254:
	ds_read_b128 v[152:155], v149
	ds_read_b128 v[156:159], v149 offset:1024
	ds_read_b128 v[160:163], v149 offset:2048
	ds_read_b128 v[164:167], v149 offset:3072
	ds_read_b128 v[168:171], v150
	ds_read_b128 v[172:175], v150 offset:1024
	ds_read_b128 v[176:179], v150 offset:2048
	ds_read_b128 v[180:183], v150 offset:3072
	ds_read_b128 v[184:187], v151
	ds_read_b128 v[188:191], v151 offset:1024
	ds_read_b128 v[192:195], v151 offset:2048
	ds_read_b128 v[196:199], v151 offset:3072
	ds_read_b128 v[200:203], v151 offset:4096
	ds_read_b128 v[204:207], v151 offset:5120
	ds_read_b128 v[208:211], v151 offset:6144
	ds_read_b128 v[212:215], v151 offset:7168
	s_add_u32 s26, s24, 0x100
	s_addc_u32 s27, s25, 0
	s_cmp_eq_u32 s67, 8
	s_cselect_b32 s31, s1, s27
	s_cselect_b32 s30, s0, s26
	s_cselect_b32 s29, s23, s66
	s_cselect_b32 s28, s22, s65
	v_lshl_add_u64 v[144:145], s[24:25], 0, v[138:139]
	s_add_i32 m0, s46, 0xc000
	s_nop 0
	global_load_lds_dwordx4 v[144:145], off
	v_lshl_add_u64 v[144:145], s[24:25], 0, v[136:137]
	s_add_i32 m0, s46, 0xe000
	s_nop 0
	global_load_lds_dwordx4 v[144:145], off
	s_waitcnt vmcnt(8)
	s_waitcnt lgkmcnt(0)
	s_barrier
	s_waitcnt lgkmcnt(0)
	v_mfma_f32_16x16x32_bf16 v[124:127], v[152:155], v[184:187], v[124:127]
	v_mfma_f32_16x16x32_bf16 v[120:123], v[160:163], v[184:187], v[120:123]
	v_mfma_f32_16x16x32_bf16 v[116:119], v[152:155], v[192:195], v[116:119]
	v_mfma_f32_16x16x32_bf16 v[108:111], v[160:163], v[192:195], v[108:111]
	s_add_i32 s24, s55, s40
	v_mfma_f32_16x16x32_bf16 v[100:103], v[152:155], v[200:203], v[100:103]
	v_mfma_f32_16x16x32_bf16 v[92:95], v[160:163], v[200:203], v[92:95]
	v_lshl_add_u64 v[144:145], s[28:29], 0, v[132:133]
	v_mfma_f32_16x16x32_bf16 v[84:87], v[152:155], v[208:211], v[84:87]
	v_mfma_f32_16x16x32_bf16 v[76:79], v[160:163], v[208:211], v[76:79]
	v_lshl_add_u64 v[216:217], s[28:29], 0, v[128:129]
	v_mfma_f32_16x16x32_bf16 v[124:127], v[156:159], v[188:191], v[124:127]
	v_mfma_f32_16x16x32_bf16 v[120:123], v[164:167], v[188:191], v[120:123]
	s_add_i32 s68, s56, s40
	v_mfma_f32_16x16x32_bf16 v[116:119], v[156:159], v[196:199], v[116:119]
	v_mfma_f32_16x16x32_bf16 v[108:111], v[164:167], v[196:199], v[108:111]
	v_lshl_add_u64 v[220:221], s[30:31], 0, v[130:131]
	v_mfma_f32_16x16x32_bf16 v[100:103], v[156:159], v[204:207], v[100:103]
	v_mfma_f32_16x16x32_bf16 v[92:95], v[164:167], v[204:207], v[92:95]
	v_lshl_add_u64 v[218:219], s[30:31], 0, v[134:135]
	v_mfma_f32_16x16x32_bf16 v[84:87], v[156:159], v[212:215], v[84:87]
	v_mfma_f32_16x16x32_bf16 v[76:79], v[164:167], v[212:215], v[76:79]
	v_mfma_f32_16x16x32_bf16 v[112:115], v[168:171], v[184:187], v[112:115]
	v_mfma_f32_16x16x32_bf16 v[104:107], v[176:179], v[184:187], v[104:107]
	v_mfma_f32_16x16x32_bf16 v[96:99], v[168:171], v[192:195], v[96:99]
	v_mfma_f32_16x16x32_bf16 v[88:91], v[176:179], v[192:195], v[88:91]
	v_mfma_f32_16x16x32_bf16 v[80:83], v[168:171], v[200:203], v[80:83]
	v_mfma_f32_16x16x32_bf16 v[72:75], v[176:179], v[200:203], v[72:75]
	v_mfma_f32_16x16x32_bf16 v[68:71], v[168:171], v[208:211], v[68:71]
	v_mfma_f32_16x16x32_bf16 v[64:67], v[176:179], v[208:211], v[64:67]
	v_mfma_f32_16x16x32_bf16 v[112:115], v[172:175], v[188:191], v[112:115]
	v_mfma_f32_16x16x32_bf16 v[104:107], v[180:183], v[188:191], v[104:107]
	v_mfma_f32_16x16x32_bf16 v[96:99], v[172:175], v[196:199], v[96:99]
	v_mfma_f32_16x16x32_bf16 v[88:91], v[180:183], v[196:199], v[88:91]
	v_mfma_f32_16x16x32_bf16 v[80:83], v[172:175], v[204:207], v[80:83]
	v_mfma_f32_16x16x32_bf16 v[72:75], v[180:183], v[204:207], v[72:75]
	v_mfma_f32_16x16x32_bf16 v[68:71], v[172:175], v[212:215], v[68:71]
	v_mfma_f32_16x16x32_bf16 v[64:67], v[180:183], v[212:215], v[64:67]
	s_barrier
	ds_read_b128 v[184:187], v151 offset:16384
	ds_read_b128 v[188:191], v151 offset:17408
	ds_read_b128 v[192:195], v151 offset:18432
	ds_read_b128 v[196:199], v151 offset:19456
	ds_read_b128 v[200:203], v151 offset:20480
	ds_read_b128 v[204:207], v151 offset:21504
	ds_read_b128 v[208:211], v151 offset:22528
	ds_read_b128 v[212:215], v151 offset:23552
	s_mov_b32 m0, s24
	s_nop 0
	global_load_lds_dwordx4 v[144:145], off
	s_add_i32 m0, s24, 0x2000
	s_add_u32 s24, s28, 0x30000
	s_addc_u32 s25, s29, 0
	global_load_lds_dwordx4 v[216:217], off
	v_lshl_add_u64 v[248:249], s[24:25], 0, v[132:133]
	s_mov_b32 m0, s68
	s_nop 0
	global_load_lds_dwordx4 v[248:249], off
	v_lshl_add_u64 v[250:251], s[24:25], 0, v[128:129]
	s_add_i32 m0, s68, 0x2000
	s_nop 0
	global_load_lds_dwordx4 v[250:251], off
	s_mov_b32 m0, s46
	s_nop 0
	global_load_lds_dwordx4 v[218:219], off
	s_mov_b32 m0, s47
	s_nop 0
	global_load_lds_dwordx4 v[220:221], off
	s_waitcnt vmcnt(8)
	s_waitcnt lgkmcnt(0)
	s_barrier
	s_waitcnt lgkmcnt(0)
	v_mfma_f32_16x16x32_bf16 v[60:63], v[152:155], v[184:187], v[60:63]
	v_mfma_f32_16x16x32_bf16 v[56:59], v[160:163], v[184:187], v[56:59]
	v_mfma_f32_16x16x32_bf16 v[52:55], v[152:155], v[192:195], v[52:55]
	v_mfma_f32_16x16x32_bf16 v[44:47], v[160:163], v[192:195], v[44:47]
	s_add_i32 s68, 0, 0x18000
	v_mfma_f32_16x16x32_bf16 v[36:39], v[152:155], v[200:203], v[36:39]
	v_mfma_f32_16x16x32_bf16 v[28:31], v[160:163], v[200:203], v[28:31]
	s_add_i32 s69, 0, 0x1c000
	v_mfma_f32_16x16x32_bf16 v[20:23], v[152:155], v[208:211], v[20:23]
	v_mfma_f32_16x16x32_bf16 v[12:15], v[160:163], v[208:211], v[12:15]
	s_add_u32 s24, s30, 0xc0000
	v_mfma_f32_16x16x32_bf16 v[60:63], v[156:159], v[188:191], v[60:63]
	v_mfma_f32_16x16x32_bf16 v[56:59], v[164:167], v[188:191], v[56:59]
	s_addc_u32 s25, s31, 0
	v_mfma_f32_16x16x32_bf16 v[52:55], v[156:159], v[196:199], v[52:55]
	v_mfma_f32_16x16x32_bf16 v[44:47], v[164:167], v[196:199], v[44:47]
	v_lshl_add_u64 v[248:249], s[24:25], 0, v[134:135]
	v_mfma_f32_16x16x32_bf16 v[36:39], v[156:159], v[204:207], v[36:39]
	v_mfma_f32_16x16x32_bf16 v[28:31], v[164:167], v[204:207], v[28:31]
	v_lshl_add_u64 v[222:223], s[24:25], 0, v[130:131]
	v_mfma_f32_16x16x32_bf16 v[20:23], v[156:159], v[212:215], v[20:23]
	v_mfma_f32_16x16x32_bf16 v[12:15], v[164:167], v[212:215], v[12:15]
	v_mfma_f32_16x16x32_bf16 v[48:51], v[168:171], v[184:187], v[48:51]
	v_mfma_f32_16x16x32_bf16 v[40:43], v[176:179], v[184:187], v[40:43]
	v_mfma_f32_16x16x32_bf16 v[32:35], v[168:171], v[192:195], v[32:35]
	v_mfma_f32_16x16x32_bf16 v[24:27], v[176:179], v[192:195], v[24:27]
	v_mfma_f32_16x16x32_bf16 v[16:19], v[168:171], v[200:203], v[16:19]
	v_mfma_f32_16x16x32_bf16 v[8:11], v[176:179], v[200:203], v[8:11]
	v_mfma_f32_16x16x32_bf16 v[4:7], v[168:171], v[208:211], v[4:7]
	v_mfma_f32_16x16x32_bf16 v[0:3], v[176:179], v[208:211], v[0:3]
	v_mfma_f32_16x16x32_bf16 v[48:51], v[172:175], v[188:191], v[48:51]
	v_mfma_f32_16x16x32_bf16 v[40:43], v[180:183], v[188:191], v[40:43]
	v_mfma_f32_16x16x32_bf16 v[32:35], v[172:175], v[196:199], v[32:35]
	v_mfma_f32_16x16x32_bf16 v[24:27], v[180:183], v[196:199], v[24:27]
	v_mfma_f32_16x16x32_bf16 v[16:19], v[172:175], v[204:207], v[16:19]
	v_mfma_f32_16x16x32_bf16 v[8:11], v[180:183], v[204:207], v[8:11]
	v_mfma_f32_16x16x32_bf16 v[4:7], v[172:175], v[212:215], v[4:7]
	v_mfma_f32_16x16x32_bf16 v[0:3], v[180:183], v[212:215], v[0:3]
	s_barrier
	ds_read_b128 v[184:187], v151 offset:32768
	ds_read_b128 v[188:191], v151 offset:33792
	ds_read_b128 v[192:195], v151 offset:34816
	ds_read_b128 v[196:199], v151 offset:35840
	ds_read_b128 v[200:203], v151 offset:36864
	ds_read_b128 v[204:207], v151 offset:37888
	ds_read_b128 v[208:211], v151 offset:38912
	ds_read_b128 v[212:215], v151 offset:39936
	v_add_u32_e32 v164, s68, v147
	v_add_u32_e32 v180, s69, v147
	ds_read_b128 v[152:155], v164
	ds_read_b128 v[156:159], v164 offset:1024
	ds_read_b128 v[160:163], v164 offset:2048
	ds_read_b128 v[164:167], v164 offset:3072
	ds_read_b128 v[168:171], v180
	ds_read_b128 v[172:175], v180 offset:1024
	ds_read_b128 v[176:179], v180 offset:2048
	ds_read_b128 v[180:183], v180 offset:3072
	s_mov_b32 m0, s48
	s_nop 0
	global_load_lds_dwordx4 v[248:249], off
	s_mov_b32 m0, s49
	s_nop 0
	global_load_lds_dwordx4 v[222:223], off
	s_waitcnt vmcnt(8)
	s_waitcnt lgkmcnt(0)
	s_barrier
	s_waitcnt lgkmcnt(0)
	v_mfma_f32_16x16x32_bf16 v[124:127], v[152:155], v[184:187], v[124:127]
	v_mfma_f32_16x16x32_bf16 v[120:123], v[160:163], v[184:187], v[120:123]
	v_mfma_f32_16x16x32_bf16 v[116:119], v[152:155], v[192:195], v[116:119]
	v_mfma_f32_16x16x32_bf16 v[108:111], v[160:163], v[192:195], v[108:111]
	s_add_i32 s24, s68, s40
	v_mfma_f32_16x16x32_bf16 v[100:103], v[152:155], v[200:203], v[100:103]
	v_mfma_f32_16x16x32_bf16 v[92:95], v[160:163], v[200:203], v[92:95]
	v_lshl_add_u64 v[248:249], v[144:145], 0, s[10:11]
	v_mfma_f32_16x16x32_bf16 v[84:87], v[152:155], v[208:211], v[84:87]
	v_mfma_f32_16x16x32_bf16 v[76:79], v[160:163], v[208:211], v[76:79]
	v_lshl_add_u64 v[250:251], v[216:217], 0, s[10:11]
	v_mfma_f32_16x16x32_bf16 v[124:127], v[156:159], v[188:191], v[124:127]
	v_mfma_f32_16x16x32_bf16 v[120:123], v[164:167], v[188:191], v[120:123]
	v_lshl_add_u64 v[246:247], v[218:219], 0, s[10:11]
	v_mfma_f32_16x16x32_bf16 v[116:119], v[156:159], v[196:199], v[116:119]
	v_mfma_f32_16x16x32_bf16 v[108:111], v[164:167], v[196:199], v[108:111]
	v_lshl_add_u64 v[144:145], v[220:221], 0, s[10:11]
	v_mfma_f32_16x16x32_bf16 v[100:103], v[156:159], v[204:207], v[100:103]
	v_mfma_f32_16x16x32_bf16 v[92:95], v[164:167], v[204:207], v[92:95]
	v_mfma_f32_16x16x32_bf16 v[84:87], v[156:159], v[212:215], v[84:87]
	v_mfma_f32_16x16x32_bf16 v[76:79], v[164:167], v[212:215], v[76:79]
	v_mfma_f32_16x16x32_bf16 v[112:115], v[168:171], v[184:187], v[112:115]
	v_mfma_f32_16x16x32_bf16 v[104:107], v[176:179], v[184:187], v[104:107]
	v_mfma_f32_16x16x32_bf16 v[96:99], v[168:171], v[192:195], v[96:99]
	v_mfma_f32_16x16x32_bf16 v[88:91], v[176:179], v[192:195], v[88:91]
	v_mfma_f32_16x16x32_bf16 v[80:83], v[168:171], v[200:203], v[80:83]
	v_mfma_f32_16x16x32_bf16 v[72:75], v[176:179], v[200:203], v[72:75]
	v_mfma_f32_16x16x32_bf16 v[68:71], v[168:171], v[208:211], v[68:71]
	v_mfma_f32_16x16x32_bf16 v[64:67], v[176:179], v[208:211], v[64:67]
	v_mfma_f32_16x16x32_bf16 v[112:115], v[172:175], v[188:191], v[112:115]
	v_mfma_f32_16x16x32_bf16 v[104:107], v[180:183], v[188:191], v[104:107]
	v_mfma_f32_16x16x32_bf16 v[96:99], v[172:175], v[196:199], v[96:99]
	v_mfma_f32_16x16x32_bf16 v[88:91], v[180:183], v[196:199], v[88:91]
	v_mfma_f32_16x16x32_bf16 v[80:83], v[172:175], v[204:207], v[80:83]
	v_mfma_f32_16x16x32_bf16 v[72:75], v[180:183], v[204:207], v[72:75]
	v_mfma_f32_16x16x32_bf16 v[68:71], v[172:175], v[212:215], v[68:71]
	v_mfma_f32_16x16x32_bf16 v[64:67], v[180:183], v[212:215], v[64:67]
	s_barrier
	ds_read_b128 v[184:187], v151 offset:49152
	ds_read_b128 v[188:191], v151 offset:50176
	ds_read_b128 v[192:195], v151 offset:51200
	ds_read_b128 v[196:199], v151 offset:52224
	ds_read_b128 v[200:203], v151 offset:53248
	ds_read_b128 v[204:207], v151 offset:54272
	ds_read_b128 v[208:211], v151 offset:55296
	ds_read_b128 v[212:215], v151 offset:56320
	s_mov_b32 m0, s24
	s_nop 0
	global_load_lds_dwordx4 v[248:249], off
	s_add_i32 m0, s24, 0x2000
	s_add_u32 s24, s28, 0x30080
	s_addc_u32 s25, s29, 0
	s_add_i32 s28, s69, s40
	global_load_lds_dwordx4 v[250:251], off
	v_lshl_add_u64 v[252:253], s[24:25], 0, v[132:133]
	s_mov_b32 m0, s28
	s_nop 0
	global_load_lds_dwordx4 v[252:253], off
	v_lshl_add_u64 v[244:245], s[24:25], 0, v[128:129]
	s_add_i32 m0, s28, 0x2000
	s_nop 0
	global_load_lds_dwordx4 v[244:245], off
	s_mov_b32 m0, s52
	s_nop 0
	global_load_lds_dwordx4 v[246:247], off
	s_mov_b32 m0, s53
	s_nop 0
	global_load_lds_dwordx4 v[144:145], off
	s_waitcnt vmcnt(8)
	s_waitcnt lgkmcnt(0)
	s_barrier
	s_waitcnt lgkmcnt(0)
	v_mfma_f32_16x16x32_bf16 v[60:63], v[152:155], v[184:187], v[60:63]
	v_mfma_f32_16x16x32_bf16 v[56:59], v[160:163], v[184:187], v[56:59]
	v_mfma_f32_16x16x32_bf16 v[52:55], v[152:155], v[192:195], v[52:55]
	v_mfma_f32_16x16x32_bf16 v[44:47], v[160:163], v[192:195], v[44:47]
	v_mfma_f32_16x16x32_bf16 v[36:39], v[152:155], v[200:203], v[36:39]
	v_mfma_f32_16x16x32_bf16 v[28:31], v[160:163], v[200:203], v[28:31]
	v_mfma_f32_16x16x32_bf16 v[20:23], v[152:155], v[208:211], v[20:23]
	v_mfma_f32_16x16x32_bf16 v[12:15], v[160:163], v[208:211], v[12:15]
	v_mfma_f32_16x16x32_bf16 v[60:63], v[156:159], v[188:191], v[60:63]
	v_mfma_f32_16x16x32_bf16 v[56:59], v[164:167], v[188:191], v[56:59]
	v_mfma_f32_16x16x32_bf16 v[52:55], v[156:159], v[196:199], v[52:55]
	v_mfma_f32_16x16x32_bf16 v[44:47], v[164:167], v[196:199], v[44:47]
	v_mfma_f32_16x16x32_bf16 v[36:39], v[156:159], v[204:207], v[36:39]
	v_mfma_f32_16x16x32_bf16 v[28:31], v[164:167], v[204:207], v[28:31]
	v_mfma_f32_16x16x32_bf16 v[20:23], v[156:159], v[212:215], v[20:23]
	v_mfma_f32_16x16x32_bf16 v[12:15], v[164:167], v[212:215], v[12:15]
	v_mfma_f32_16x16x32_bf16 v[48:51], v[168:171], v[184:187], v[48:51]
	v_mfma_f32_16x16x32_bf16 v[40:43], v[176:179], v[184:187], v[40:43]
	v_mfma_f32_16x16x32_bf16 v[32:35], v[168:171], v[192:195], v[32:35]
	v_mfma_f32_16x16x32_bf16 v[24:27], v[176:179], v[192:195], v[24:27]
	v_mfma_f32_16x16x32_bf16 v[16:19], v[168:171], v[200:203], v[16:19]
	v_mfma_f32_16x16x32_bf16 v[8:11], v[176:179], v[200:203], v[8:11]
	v_mfma_f32_16x16x32_bf16 v[4:7], v[168:171], v[208:211], v[4:7]
	v_mfma_f32_16x16x32_bf16 v[0:3], v[176:179], v[208:211], v[0:3]
	v_mfma_f32_16x16x32_bf16 v[48:51], v[172:175], v[188:191], v[48:51]
	v_mfma_f32_16x16x32_bf16 v[40:43], v[180:183], v[188:191], v[40:43]
	v_mfma_f32_16x16x32_bf16 v[32:35], v[172:175], v[196:199], v[32:35]
	v_mfma_f32_16x16x32_bf16 v[24:27], v[180:183], v[196:199], v[24:27]
	v_mfma_f32_16x16x32_bf16 v[16:19], v[172:175], v[204:207], v[16:19]
	v_mfma_f32_16x16x32_bf16 v[8:11], v[180:183], v[204:207], v[8:11]
	v_mfma_f32_16x16x32_bf16 v[4:7], v[172:175], v[212:215], v[4:7]
	v_mfma_f32_16x16x32_bf16 v[0:3], v[180:183], v[212:215], v[0:3]
	s_barrier
	s_add_i32 s67, s67, 2
	s_add_u32 s65, s65, 0x100
	s_addc_u32 s66, s66, 0
	s_cmp_gt_u32 s67, 9
	s_mov_b64 s[24:25], s[26:27]
	s_cbranch_scc0 .LBB0_254
	s_setprio 0
	s_and_b64 vcc, exec, s[12:13]
	s_cbranch_vccz .LBB0_257
	s_barrier

.Lsp_skip2:
.LBB0_281:
	ds_read_b128 v[144:147], v153
	ds_read_b128 v[156:159], v153 offset:1024
	ds_read_b128 v[160:163], v153 offset:2048
	ds_read_b128 v[164:167], v153 offset:3072
	ds_read_b128 v[168:171], v154
	ds_read_b128 v[172:175], v154 offset:1024
	ds_read_b128 v[176:179], v154 offset:2048
	ds_read_b128 v[180:183], v154 offset:3072
	ds_read_b128 v[184:187], v155
	ds_read_b128 v[188:191], v155 offset:1024
	ds_read_b128 v[192:195], v155 offset:2048
	ds_read_b128 v[196:199], v155 offset:3072
	ds_read_b128 v[200:203], v155 offset:4096
	ds_read_b128 v[204:207], v155 offset:5120
	ds_read_b128 v[208:211], v155 offset:6144
	ds_read_b128 v[212:215], v155 offset:7168
	s_add_u32 s34, s30, 0xfff80080
	s_addc_u32 s35, s31, -1
	s_cmp_eq_u32 s61, 28
	s_cselect_b32 s37, s23, s35
	s_cselect_b32 s36, s57, s34
	s_cselect_b32 s35, s21, s60
	s_cselect_b32 s34, s58, s59
	v_lshl_add_u64 v[148:149], s[30:31], 0, v[138:139]
	s_add_i32 m0, s29, 0xc000
	s_nop 0
	global_load_lds_dwordx4 v[148:149], off
	v_lshl_add_u64 v[148:149], s[30:31], 0, v[136:137]
	s_add_i32 m0, s29, 0xe000
	s_nop 0
	global_load_lds_dwordx4 v[148:149], off
	s_waitcnt vmcnt(8)
	s_waitcnt lgkmcnt(0)
	s_barrier
	s_waitcnt lgkmcnt(0)
	v_mfma_i32_16x16x64_i8 v[124:127], v[144:147], v[184:187], v[124:127]
	v_mfma_i32_16x16x64_i8 v[120:123], v[160:163], v[184:187], v[120:123]
	v_mfma_i32_16x16x64_i8 v[108:111], v[144:147], v[192:195], v[108:111]
	v_mfma_i32_16x16x64_i8 v[104:107], v[160:163], v[192:195], v[104:107]
	s_add_i32 s62, s41, s40
	v_mfma_i32_16x16x64_i8 v[92:95], v[144:147], v[200:203], v[92:95]
	v_mfma_i32_16x16x64_i8 v[88:91], v[160:163], v[200:203], v[88:91]
	v_lshl_add_u64 v[148:149], s[34:35], 0, v[130:131]
	v_mfma_i32_16x16x64_i8 v[76:79], v[144:147], v[208:211], v[76:79]
	v_mfma_i32_16x16x64_i8 v[72:75], v[160:163], v[208:211], v[72:75]
	v_lshl_add_u64 v[216:217], s[34:35], 0, v[134:135]
	v_mfma_i32_16x16x64_i8 v[124:127], v[156:159], v[188:191], v[124:127]
	v_mfma_i32_16x16x64_i8 v[120:123], v[164:167], v[188:191], v[120:123]
	s_add_i32 s64, s42, s40
	v_mfma_i32_16x16x64_i8 v[108:111], v[156:159], v[196:199], v[108:111]
	v_mfma_i32_16x16x64_i8 v[104:107], v[164:167], v[196:199], v[104:107]
	v_lshl_add_u64 v[220:221], s[36:37], 0, v[132:133]
	v_mfma_i32_16x16x64_i8 v[92:95], v[156:159], v[204:207], v[92:95]
	v_mfma_i32_16x16x64_i8 v[88:91], v[164:167], v[204:207], v[88:91]
	v_lshl_add_u64 v[218:219], s[36:37], 0, v[128:129]
	v_mfma_i32_16x16x64_i8 v[76:79], v[156:159], v[212:215], v[76:79]
	v_mfma_i32_16x16x64_i8 v[72:75], v[164:167], v[212:215], v[72:75]
	v_mfma_i32_16x16x64_i8 v[116:119], v[168:171], v[184:187], v[116:119]
	v_mfma_i32_16x16x64_i8 v[112:115], v[176:179], v[184:187], v[112:115]
	v_mfma_i32_16x16x64_i8 v[100:103], v[168:171], v[192:195], v[100:103]
	v_mfma_i32_16x16x64_i8 v[96:99], v[176:179], v[192:195], v[96:99]
	v_mfma_i32_16x16x64_i8 v[84:87], v[168:171], v[200:203], v[84:87]
	v_mfma_i32_16x16x64_i8 v[80:83], v[176:179], v[200:203], v[80:83]
	v_mfma_i32_16x16x64_i8 v[68:71], v[168:171], v[208:211], v[68:71]
	v_mfma_i32_16x16x64_i8 v[64:67], v[176:179], v[208:211], v[64:67]
	v_mfma_i32_16x16x64_i8 v[116:119], v[172:175], v[188:191], v[116:119]
	v_mfma_i32_16x16x64_i8 v[112:115], v[180:183], v[188:191], v[112:115]
	v_mfma_i32_16x16x64_i8 v[100:103], v[172:175], v[196:199], v[100:103]
	v_mfma_i32_16x16x64_i8 v[96:99], v[180:183], v[196:199], v[96:99]
	v_mfma_i32_16x16x64_i8 v[84:87], v[172:175], v[204:207], v[84:87]
	v_mfma_i32_16x16x64_i8 v[80:83], v[180:183], v[204:207], v[80:83]
	v_mfma_i32_16x16x64_i8 v[68:71], v[172:175], v[212:215], v[68:71]
	v_mfma_i32_16x16x64_i8 v[64:67], v[180:183], v[212:215], v[64:67]
	s_barrier
	ds_read_b128 v[184:187], v155 offset:16384
	ds_read_b128 v[188:191], v155 offset:17408
	ds_read_b128 v[192:195], v155 offset:18432
	ds_read_b128 v[196:199], v155 offset:19456
	ds_read_b128 v[200:203], v155 offset:20480
	ds_read_b128 v[204:207], v155 offset:21504
	ds_read_b128 v[208:211], v155 offset:22528
	ds_read_b128 v[212:215], v155 offset:23552
	s_mov_b32 m0, s62
	s_nop 0
	global_load_lds_dwordx4 v[148:149], off
	s_add_i32 m0, s62, 0x2000
	s_add_u32 s62, s34, 0x80000
	s_addc_u32 s63, s35, 0
	global_load_lds_dwordx4 v[216:217], off
	v_lshl_add_u64 v[248:249], s[62:63], 0, v[130:131]
	s_mov_b32 m0, s64
	s_nop 0
	global_load_lds_dwordx4 v[248:249], off
	v_lshl_add_u64 v[250:251], s[62:63], 0, v[134:135]
	s_add_i32 m0, s64, 0x2000
	s_nop 0
	global_load_lds_dwordx4 v[250:251], off
	s_mov_b32 m0, s29
	s_nop 0
	global_load_lds_dwordx4 v[218:219], off
	s_mov_b32 m0, s48
	s_nop 0
	global_load_lds_dwordx4 v[220:221], off
	s_waitcnt vmcnt(8)
	s_waitcnt lgkmcnt(0)
	s_barrier
	s_waitcnt lgkmcnt(0)
	v_mfma_i32_16x16x64_i8 v[60:63], v[144:147], v[184:187], v[60:63]
	v_mfma_i32_16x16x64_i8 v[56:59], v[160:163], v[184:187], v[56:59]
	v_mfma_i32_16x16x64_i8 v[44:47], v[144:147], v[192:195], v[44:47]
	v_mfma_i32_16x16x64_i8 v[40:43], v[160:163], v[192:195], v[40:43]
	s_add_i32 s62, 0, 0x18000
	v_mfma_i32_16x16x64_i8 v[28:31], v[144:147], v[200:203], v[28:31]
	v_mfma_i32_16x16x64_i8 v[24:27], v[160:163], v[200:203], v[24:27]
	s_add_i32 s63, 0, 0x1c000
	v_mfma_i32_16x16x64_i8 v[12:15], v[144:147], v[208:211], v[12:15]
	v_mfma_i32_16x16x64_i8 v[8:11], v[160:163], v[208:211], v[8:11]
	s_add_u32 s36, s36, 0x80000
	v_mfma_i32_16x16x64_i8 v[60:63], v[156:159], v[188:191], v[60:63]
	v_mfma_i32_16x16x64_i8 v[56:59], v[164:167], v[188:191], v[56:59]
	s_addc_u32 s37, s37, 0
	v_mfma_i32_16x16x64_i8 v[44:47], v[156:159], v[196:199], v[44:47]
	v_mfma_i32_16x16x64_i8 v[40:43], v[164:167], v[196:199], v[40:43]
	v_lshl_add_u64 v[248:249], s[36:37], 0, v[128:129]
	v_mfma_i32_16x16x64_i8 v[28:31], v[156:159], v[204:207], v[28:31]
	v_mfma_i32_16x16x64_i8 v[24:27], v[164:167], v[204:207], v[24:27]
	v_lshl_add_u64 v[222:223], s[36:37], 0, v[132:133]
	v_mfma_i32_16x16x64_i8 v[12:15], v[156:159], v[212:215], v[12:15]
	v_mfma_i32_16x16x64_i8 v[8:11], v[164:167], v[212:215], v[8:11]
	v_mfma_i32_16x16x64_i8 v[52:55], v[168:171], v[184:187], v[52:55]
	v_mfma_i32_16x16x64_i8 v[48:51], v[176:179], v[184:187], v[48:51]
	v_mfma_i32_16x16x64_i8 v[36:39], v[168:171], v[192:195], v[36:39]
	v_mfma_i32_16x16x64_i8 v[32:35], v[176:179], v[192:195], v[32:35]
	v_mfma_i32_16x16x64_i8 v[20:23], v[168:171], v[200:203], v[20:23]
	v_mfma_i32_16x16x64_i8 v[16:19], v[176:179], v[200:203], v[16:19]
	v_mfma_i32_16x16x64_i8 v[4:7], v[168:171], v[208:211], v[4:7]
	v_mfma_i32_16x16x64_i8 v[0:3], v[176:179], v[208:211], v[0:3]
	v_mfma_i32_16x16x64_i8 v[52:55], v[172:175], v[188:191], v[52:55]
	v_mfma_i32_16x16x64_i8 v[48:51], v[180:183], v[188:191], v[48:51]
	v_mfma_i32_16x16x64_i8 v[36:39], v[172:175], v[196:199], v[36:39]
	v_mfma_i32_16x16x64_i8 v[32:35], v[180:183], v[196:199], v[32:35]
	v_mfma_i32_16x16x64_i8 v[20:23], v[172:175], v[204:207], v[20:23]
	v_mfma_i32_16x16x64_i8 v[16:19], v[180:183], v[204:207], v[16:19]
	v_mfma_i32_16x16x64_i8 v[4:7], v[172:175], v[212:215], v[4:7]
	v_mfma_i32_16x16x64_i8 v[0:3], v[180:183], v[212:215], v[0:3]
	s_barrier
	ds_read_b128 v[184:187], v155 offset:32768
	ds_read_b128 v[188:191], v155 offset:33792
	ds_read_b128 v[192:195], v155 offset:34816
	ds_read_b128 v[196:199], v155 offset:35840
	ds_read_b128 v[200:203], v155 offset:36864
	ds_read_b128 v[204:207], v155 offset:37888
	ds_read_b128 v[208:211], v155 offset:38912
	ds_read_b128 v[212:215], v155 offset:39936
	v_add_u32_e32 v164, s62, v151
	v_add_u32_e32 v180, s63, v151
	ds_read_b128 v[144:147], v164
	ds_read_b128 v[156:159], v164 offset:1024
	ds_read_b128 v[160:163], v164 offset:2048
	ds_read_b128 v[164:167], v164 offset:3072
	ds_read_b128 v[168:171], v180
	ds_read_b128 v[172:175], v180 offset:1024
	ds_read_b128 v[176:179], v180 offset:2048
	ds_read_b128 v[180:183], v180 offset:3072
	s_mov_b32 m0, s49
	s_nop 0
	global_load_lds_dwordx4 v[248:249], off
	s_mov_b32 m0, s50
	s_nop 0
	global_load_lds_dwordx4 v[222:223], off
	s_waitcnt vmcnt(8)
	s_waitcnt lgkmcnt(0)
	s_barrier
	s_waitcnt lgkmcnt(0)
	v_mfma_i32_16x16x64_i8 v[124:127], v[144:147], v[184:187], v[124:127]
	v_mfma_i32_16x16x64_i8 v[120:123], v[160:163], v[184:187], v[120:123]
	v_mfma_i32_16x16x64_i8 v[108:111], v[144:147], v[192:195], v[108:111]
	v_mfma_i32_16x16x64_i8 v[104:107], v[160:163], v[192:195], v[104:107]
	s_add_i32 s36, s62, s40
	v_mfma_i32_16x16x64_i8 v[92:95], v[144:147], v[200:203], v[92:95]
	v_mfma_i32_16x16x64_i8 v[88:91], v[160:163], v[200:203], v[88:91]
	v_lshl_add_u64 v[248:249], v[148:149], 0, s[6:7]
	v_mfma_i32_16x16x64_i8 v[76:79], v[144:147], v[208:211], v[76:79]
	v_mfma_i32_16x16x64_i8 v[72:75], v[160:163], v[208:211], v[72:75]
	s_add_u32 s34, s34, 0x80080
	v_mfma_i32_16x16x64_i8 v[124:127], v[156:159], v[188:191], v[124:127]
	v_mfma_i32_16x16x64_i8 v[120:123], v[164:167], v[188:191], v[120:123]
	v_lshl_add_u64 v[250:251], v[216:217], 0, s[6:7]
	v_mfma_i32_16x16x64_i8 v[108:111], v[156:159], v[196:199], v[108:111]
	v_mfma_i32_16x16x64_i8 v[104:107], v[164:167], v[196:199], v[104:107]
	s_addc_u32 s35, s35, 0
	v_mfma_i32_16x16x64_i8 v[92:95], v[156:159], v[204:207], v[92:95]
	v_mfma_i32_16x16x64_i8 v[88:91], v[164:167], v[204:207], v[88:91]
	v_lshl_add_u64 v[252:253], s[34:35], 0, v[130:131]
	v_mfma_i32_16x16x64_i8 v[76:79], v[156:159], v[212:215], v[76:79]
	v_mfma_i32_16x16x64_i8 v[72:75], v[164:167], v[212:215], v[72:75]
	v_lshl_add_u64 v[244:245], s[34:35], 0, v[134:135]
	v_mfma_i32_16x16x64_i8 v[116:119], v[168:171], v[184:187], v[116:119]
	v_mfma_i32_16x16x64_i8 v[112:115], v[176:179], v[184:187], v[112:115]
	v_lshl_add_u64 v[246:247], v[218:219], 0, s[6:7]
	v_mfma_i32_16x16x64_i8 v[100:103], v[168:171], v[192:195], v[100:103]
	v_mfma_i32_16x16x64_i8 v[96:99], v[176:179], v[192:195], v[96:99]
	v_lshl_add_u64 v[148:149], v[220:221], 0, s[6:7]
	v_mfma_i32_16x16x64_i8 v[84:87], v[168:171], v[200:203], v[84:87]
	v_mfma_i32_16x16x64_i8 v[80:83], v[176:179], v[200:203], v[80:83]
	v_mfma_i32_16x16x64_i8 v[68:71], v[168:171], v[208:211], v[68:71]
	v_mfma_i32_16x16x64_i8 v[64:67], v[176:179], v[208:211], v[64:67]
	v_mfma_i32_16x16x64_i8 v[116:119], v[172:175], v[188:191], v[116:119]
	v_mfma_i32_16x16x64_i8 v[112:115], v[180:183], v[188:191], v[112:115]
	v_mfma_i32_16x16x64_i8 v[100:103], v[172:175], v[196:199], v[100:103]
	v_mfma_i32_16x16x64_i8 v[96:99], v[180:183], v[196:199], v[96:99]
	v_mfma_i32_16x16x64_i8 v[84:87], v[172:175], v[204:207], v[84:87]
	v_mfma_i32_16x16x64_i8 v[80:83], v[180:183], v[204:207], v[80:83]
	v_mfma_i32_16x16x64_i8 v[68:71], v[172:175], v[212:215], v[68:71]
	v_mfma_i32_16x16x64_i8 v[64:67], v[180:183], v[212:215], v[64:67]
	s_barrier
	ds_read_b128 v[184:187], v155 offset:49152
	ds_read_b128 v[188:191], v155 offset:50176
	ds_read_b128 v[192:195], v155 offset:51200
	ds_read_b128 v[196:199], v155 offset:52224
	ds_read_b128 v[200:203], v155 offset:53248
	ds_read_b128 v[204:207], v155 offset:54272
	ds_read_b128 v[208:211], v155 offset:55296
	ds_read_b128 v[212:215], v155 offset:56320
	s_mov_b32 m0, s36
	s_nop 0
	global_load_lds_dwordx4 v[248:249], off
	s_add_i32 m0, s36, 0x2000
	s_add_i32 s36, s63, s40
	global_load_lds_dwordx4 v[250:251], off
	s_mov_b32 m0, s36
	s_nop 0
	global_load_lds_dwordx4 v[252:253], off
	s_add_i32 m0, s36, 0x2000
	s_nop 0
	global_load_lds_dwordx4 v[244:245], off
	s_mov_b32 m0, s44
	s_nop 0
	global_load_lds_dwordx4 v[246:247], off
	s_mov_b32 m0, s52
	s_nop 0
	global_load_lds_dwordx4 v[148:149], off
	s_waitcnt vmcnt(8)
	s_waitcnt lgkmcnt(0)
	s_barrier
	s_waitcnt lgkmcnt(0)
	v_mfma_i32_16x16x64_i8 v[60:63], v[144:147], v[184:187], v[60:63]
	v_mfma_i32_16x16x64_i8 v[56:59], v[160:163], v[184:187], v[56:59]
	v_mfma_i32_16x16x64_i8 v[44:47], v[144:147], v[192:195], v[44:47]
	v_mfma_i32_16x16x64_i8 v[40:43], v[160:163], v[192:195], v[40:43]
	v_mfma_i32_16x16x64_i8 v[28:31], v[144:147], v[200:203], v[28:31]
	v_mfma_i32_16x16x64_i8 v[24:27], v[160:163], v[200:203], v[24:27]
	v_mfma_i32_16x16x64_i8 v[12:15], v[144:147], v[208:211], v[12:15]
	v_mfma_i32_16x16x64_i8 v[8:11], v[160:163], v[208:211], v[8:11]
	v_mfma_i32_16x16x64_i8 v[60:63], v[156:159], v[188:191], v[60:63]
	v_mfma_i32_16x16x64_i8 v[56:59], v[164:167], v[188:191], v[56:59]
	v_mfma_i32_16x16x64_i8 v[44:47], v[156:159], v[196:199], v[44:47]
	v_mfma_i32_16x16x64_i8 v[40:43], v[164:167], v[196:199], v[40:43]
	v_mfma_i32_16x16x64_i8 v[28:31], v[156:159], v[204:207], v[28:31]
	v_mfma_i32_16x16x64_i8 v[24:27], v[164:167], v[204:207], v[24:27]
	v_mfma_i32_16x16x64_i8 v[12:15], v[156:159], v[212:215], v[12:15]
	v_mfma_i32_16x16x64_i8 v[8:11], v[164:167], v[212:215], v[8:11]
	v_mfma_i32_16x16x64_i8 v[52:55], v[168:171], v[184:187], v[52:55]
	v_mfma_i32_16x16x64_i8 v[48:51], v[176:179], v[184:187], v[48:51]
	v_mfma_i32_16x16x64_i8 v[36:39], v[168:171], v[192:195], v[36:39]
	v_mfma_i32_16x16x64_i8 v[32:35], v[176:179], v[192:195], v[32:35]
	v_mfma_i32_16x16x64_i8 v[20:23], v[168:171], v[200:203], v[20:23]
	v_mfma_i32_16x16x64_i8 v[16:19], v[176:179], v[200:203], v[16:19]
	v_mfma_i32_16x16x64_i8 v[4:7], v[168:171], v[208:211], v[4:7]
	v_mfma_i32_16x16x64_i8 v[0:3], v[176:179], v[208:211], v[0:3]
	v_mfma_i32_16x16x64_i8 v[52:55], v[172:175], v[188:191], v[52:55]
	v_mfma_i32_16x16x64_i8 v[48:51], v[180:183], v[188:191], v[48:51]
	v_mfma_i32_16x16x64_i8 v[36:39], v[172:175], v[196:199], v[36:39]
	v_mfma_i32_16x16x64_i8 v[32:35], v[180:183], v[196:199], v[32:35]
	v_mfma_i32_16x16x64_i8 v[20:23], v[172:175], v[204:207], v[20:23]
	v_mfma_i32_16x16x64_i8 v[16:19], v[180:183], v[204:207], v[16:19]
	v_mfma_i32_16x16x64_i8 v[4:7], v[172:175], v[212:215], v[4:7]
	v_mfma_i32_16x16x64_i8 v[0:3], v[180:183], v[212:215], v[0:3]
	s_barrier
	s_add_i32 s61, s61, 2
	s_add_u32 s59, s59, 0x100
	s_addc_u32 s60, s60, 0
	s_add_u32 s30, s30, 0x100
	s_addc_u32 s31, s31, 0
	s_cmp_gt_u32 s61, 29
	s_cbranch_scc0 .LBB0_281
	s_setprio 0
	s_and_b64 vcc, exec, s[8:9]
	s_cbranch_vccz .LBB0_284
	s_barrier

.Lsp_skip3:
.LBB0_451:
	ds_read_b128 v[112:115], v193
	ds_read_b128 v[124:127], v193 offset:1024
	ds_read_b128 v[136:139], v193 offset:2048
	ds_read_b128 v[140:143], v193 offset:3072
	ds_read_b128 v[144:147], v194
	ds_read_b128 v[148:151], v194 offset:1024
	ds_read_b128 v[168:171], v194 offset:2048
	ds_read_b128 v[172:175], v194 offset:3072
	ds_read_b128 v[176:179], v195
	ds_read_b128 v[180:183], v195 offset:1024
	ds_read_b128 v[184:187], v195 offset:2048
	ds_read_b128 v[200:203], v195 offset:3072
	ds_read_b128 v[204:207], v195 offset:4096
	ds_read_b128 v[208:211], v195 offset:5120
	ds_read_b128 v[212:215], v195 offset:6144
	ds_read_b128 v[216:219], v195 offset:7168
	s_add_u32 s34, s30, 0xfff00080
	s_addc_u32 s35, s31, -1
	s_cmp_eq_u32 s58, 60
	s_cselect_b32 s37, s21, s35
	s_cselect_b32 s36, s27, s34
	s_cselect_b32 s35, s19, s57
	s_cselect_b32 s34, s55, s56
	v_lshl_add_u64 v[188:189], s[30:31], 0, v[162:163]
	s_add_i32 m0, s29, 0xc000
	s_nop 0
	global_load_lds_dwordx4 v[188:189], off
	v_lshl_add_u64 v[188:189], s[30:31], 0, v[160:161]
	s_add_i32 m0, s29, 0xe000
	s_nop 0
	global_load_lds_dwordx4 v[188:189], off
	s_waitcnt vmcnt(8)
	s_waitcnt lgkmcnt(0)
	s_barrier
	s_waitcnt lgkmcnt(0)
	v_mfma_f32_16x16x32_bf16 v[132:135], v[112:115], v[176:179], v[132:135]
	v_mfma_f32_16x16x32_bf16 v[128:131], v[136:139], v[176:179], v[128:131]
	v_mfma_f32_16x16x32_bf16 v[108:111], v[112:115], v[184:187], v[108:111]
	v_mfma_f32_16x16x32_bf16 v[104:107], v[136:139], v[184:187], v[104:107]
	s_add_i32 s59, s50, s41
	v_mfma_f32_16x16x32_bf16 v[92:95], v[112:115], v[204:207], v[92:95]
	v_mfma_f32_16x16x32_bf16 v[88:91], v[136:139], v[204:207], v[88:91]
	v_lshl_add_u64 v[188:189], s[34:35], 0, v[154:155]
	v_mfma_f32_16x16x32_bf16 v[76:79], v[112:115], v[212:215], v[76:79]
	v_mfma_f32_16x16x32_bf16 v[72:75], v[136:139], v[212:215], v[72:75]
	s_add_u32 s60, s34, 0x100000
	v_mfma_f32_16x16x32_bf16 v[132:135], v[124:127], v[180:183], v[132:135]
	v_mfma_f32_16x16x32_bf16 v[128:131], v[140:143], v[180:183], v[128:131]
	v_lshl_add_u64 v[220:221], s[34:35], 0, v[158:159]
	v_mfma_f32_16x16x32_bf16 v[108:111], v[124:127], v[200:203], v[108:111]
	v_mfma_f32_16x16x32_bf16 v[104:107], v[140:143], v[200:203], v[104:107]
	s_addc_u32 s61, s35, 0
	v_mfma_f32_16x16x32_bf16 v[92:95], v[124:127], v[208:211], v[92:95]
	v_mfma_f32_16x16x32_bf16 v[88:91], v[140:143], v[208:211], v[88:91]
	v_lshl_add_u64 v[248:249], s[60:61], 0, v[154:155]
	v_mfma_f32_16x16x32_bf16 v[76:79], v[124:127], v[216:219], v[76:79]
	v_mfma_f32_16x16x32_bf16 v[72:75], v[140:143], v[216:219], v[72:75]
	v_lshl_add_u64 v[224:225], s[36:37], 0, v[156:157]
	v_mfma_f32_16x16x32_bf16 v[120:123], v[144:147], v[176:179], v[120:123]
	v_mfma_f32_16x16x32_bf16 v[116:119], v[168:171], v[176:179], v[116:119]
	v_lshl_add_u64 v[250:251], s[60:61], 0, v[158:159]
	v_mfma_f32_16x16x32_bf16 v[100:103], v[144:147], v[184:187], v[100:103]
	v_mfma_f32_16x16x32_bf16 v[96:99], v[168:171], v[184:187], v[96:99]
	v_lshl_add_u64 v[222:223], s[36:37], 0, v[152:153]
	v_mfma_f32_16x16x32_bf16 v[84:87], v[144:147], v[204:207], v[84:87]
	v_mfma_f32_16x16x32_bf16 v[80:83], v[168:171], v[204:207], v[80:83]
	v_mfma_f32_16x16x32_bf16 v[68:71], v[144:147], v[212:215], v[68:71]
	v_mfma_f32_16x16x32_bf16 v[64:67], v[168:171], v[212:215], v[64:67]
	v_mfma_f32_16x16x32_bf16 v[120:123], v[148:151], v[180:183], v[120:123]
	v_mfma_f32_16x16x32_bf16 v[116:119], v[172:175], v[180:183], v[116:119]
	v_mfma_f32_16x16x32_bf16 v[100:103], v[148:151], v[200:203], v[100:103]
	v_mfma_f32_16x16x32_bf16 v[96:99], v[172:175], v[200:203], v[96:99]
	v_mfma_f32_16x16x32_bf16 v[84:87], v[148:151], v[208:211], v[84:87]
	v_mfma_f32_16x16x32_bf16 v[80:83], v[172:175], v[208:211], v[80:83]
	v_mfma_f32_16x16x32_bf16 v[68:71], v[148:151], v[216:219], v[68:71]
	v_mfma_f32_16x16x32_bf16 v[64:67], v[172:175], v[216:219], v[64:67]
	s_barrier
	ds_read_b128 v[176:179], v195 offset:16384
	ds_read_b128 v[180:183], v195 offset:17408
	ds_read_b128 v[184:187], v195 offset:18432
	ds_read_b128 v[200:203], v195 offset:19456
	ds_read_b128 v[204:207], v195 offset:20480
	ds_read_b128 v[208:211], v195 offset:21504
	ds_read_b128 v[212:215], v195 offset:22528
	ds_read_b128 v[216:219], v195 offset:23552
	s_mov_b32 m0, s59
	s_nop 0
	global_load_lds_dwordx4 v[188:189], off
	s_add_i32 m0, s59, 0x2000
	s_add_i32 s59, s51, s41
	global_load_lds_dwordx4 v[220:221], off
	s_mov_b32 m0, s59
	s_nop 0
	global_load_lds_dwordx4 v[248:249], off
	s_add_i32 m0, s59, 0x2000
	s_nop 0
	global_load_lds_dwordx4 v[250:251], off
	s_mov_b32 m0, s29
	s_nop 0
	global_load_lds_dwordx4 v[222:223], off
	s_mov_b32 m0, s42
	s_nop 0
	global_load_lds_dwordx4 v[224:225], off
	s_waitcnt vmcnt(8)
	s_waitcnt lgkmcnt(0)
	s_barrier
	s_waitcnt lgkmcnt(0)
	v_mfma_f32_16x16x32_bf16 v[60:63], v[112:115], v[176:179], v[60:63]
	v_mfma_f32_16x16x32_bf16 v[56:59], v[136:139], v[176:179], v[56:59]
	v_mfma_f32_16x16x32_bf16 v[44:47], v[112:115], v[184:187], v[44:47]
	v_mfma_f32_16x16x32_bf16 v[40:43], v[136:139], v[184:187], v[40:43]
	s_add_i32 s59, 0, 0x18000
	v_mfma_f32_16x16x32_bf16 v[28:31], v[112:115], v[204:207], v[28:31]
	v_mfma_f32_16x16x32_bf16 v[24:27], v[136:139], v[204:207], v[24:27]
	s_add_i32 s60, 0, 0x1c000
	v_mfma_f32_16x16x32_bf16 v[12:15], v[112:115], v[212:215], v[12:15]
	v_mfma_f32_16x16x32_bf16 v[8:11], v[136:139], v[212:215], v[8:11]
	s_add_u32 s36, s36, 0x100000
	v_mfma_f32_16x16x32_bf16 v[60:63], v[124:127], v[180:183], v[60:63]
	v_mfma_f32_16x16x32_bf16 v[56:59], v[140:143], v[180:183], v[56:59]
	s_addc_u32 s37, s37, 0
	v_mfma_f32_16x16x32_bf16 v[44:47], v[124:127], v[200:203], v[44:47]
	v_mfma_f32_16x16x32_bf16 v[40:43], v[140:143], v[200:203], v[40:43]
	v_lshl_add_u64 v[248:249], s[36:37], 0, v[152:153]
	v_mfma_f32_16x16x32_bf16 v[28:31], v[124:127], v[208:211], v[28:31]
	v_mfma_f32_16x16x32_bf16 v[24:27], v[140:143], v[208:211], v[24:27]
	v_lshl_add_u64 v[226:227], s[36:37], 0, v[156:157]
	v_mfma_f32_16x16x32_bf16 v[12:15], v[124:127], v[216:219], v[12:15]
	v_mfma_f32_16x16x32_bf16 v[8:11], v[140:143], v[216:219], v[8:11]
	v_mfma_f32_16x16x32_bf16 v[52:55], v[144:147], v[176:179], v[52:55]
	v_mfma_f32_16x16x32_bf16 v[48:51], v[168:171], v[176:179], v[48:51]
	v_mfma_f32_16x16x32_bf16 v[36:39], v[144:147], v[184:187], v[36:39]
	v_mfma_f32_16x16x32_bf16 v[32:35], v[168:171], v[184:187], v[32:35]
	v_mfma_f32_16x16x32_bf16 v[20:23], v[144:147], v[204:207], v[20:23]
	v_mfma_f32_16x16x32_bf16 v[16:19], v[168:171], v[204:207], v[16:19]
	v_mfma_f32_16x16x32_bf16 v[4:7], v[144:147], v[212:215], v[4:7]
	v_mfma_f32_16x16x32_bf16 v[0:3], v[168:171], v[212:215], v[0:3]
	v_mfma_f32_16x16x32_bf16 v[52:55], v[148:151], v[180:183], v[52:55]
	v_mfma_f32_16x16x32_bf16 v[48:51], v[172:175], v[180:183], v[48:51]
	v_mfma_f32_16x16x32_bf16 v[36:39], v[148:151], v[200:203], v[36:39]
	v_mfma_f32_16x16x32_bf16 v[32:35], v[172:175], v[200:203], v[32:35]
	v_mfma_f32_16x16x32_bf16 v[20:23], v[148:151], v[208:211], v[20:23]
	v_mfma_f32_16x16x32_bf16 v[16:19], v[172:175], v[208:211], v[16:19]
	v_mfma_f32_16x16x32_bf16 v[4:7], v[148:151], v[216:219], v[4:7]
	v_mfma_f32_16x16x32_bf16 v[0:3], v[172:175], v[216:219], v[0:3]
	s_barrier
	ds_read_b128 v[176:179], v195 offset:32768
	ds_read_b128 v[180:183], v195 offset:33792
	ds_read_b128 v[184:187], v195 offset:34816
	ds_read_b128 v[200:203], v195 offset:35840
	ds_read_b128 v[204:207], v195 offset:36864
	ds_read_b128 v[208:211], v195 offset:37888
	ds_read_b128 v[212:215], v195 offset:38912
	ds_read_b128 v[216:219], v195 offset:39936
	v_add_u32_e32 v140, s59, v191
	v_add_u32_e32 v172, s60, v191
	ds_read_b128 v[112:115], v140
	ds_read_b128 v[124:127], v140 offset:1024
	ds_read_b128 v[136:139], v140 offset:2048
	ds_read_b128 v[140:143], v140 offset:3072
	ds_read_b128 v[144:147], v172
	ds_read_b128 v[148:151], v172 offset:1024
	ds_read_b128 v[168:171], v172 offset:2048
	ds_read_b128 v[172:175], v172 offset:3072
	s_mov_b32 m0, s43
	s_nop 0
	global_load_lds_dwordx4 v[248:249], off
	s_mov_b32 m0, s44
	s_nop 0
	global_load_lds_dwordx4 v[226:227], off
	s_waitcnt vmcnt(8)
	s_waitcnt lgkmcnt(0)
	s_barrier
	s_waitcnt lgkmcnt(0)
	v_mfma_f32_16x16x32_bf16 v[132:135], v[112:115], v[176:179], v[132:135]
	v_mfma_f32_16x16x32_bf16 v[128:131], v[136:139], v[176:179], v[128:131]
	v_mfma_f32_16x16x32_bf16 v[108:111], v[112:115], v[184:187], v[108:111]
	v_mfma_f32_16x16x32_bf16 v[104:107], v[136:139], v[184:187], v[104:107]
	s_add_i32 s36, s59, s41
	v_mfma_f32_16x16x32_bf16 v[92:95], v[112:115], v[204:207], v[92:95]
	v_mfma_f32_16x16x32_bf16 v[88:91], v[136:139], v[204:207], v[88:91]
	v_lshl_add_u64 v[248:249], v[188:189], 0, s[14:15]
	v_mfma_f32_16x16x32_bf16 v[76:79], v[112:115], v[212:215], v[76:79]
	v_mfma_f32_16x16x32_bf16 v[72:75], v[136:139], v[212:215], v[72:75]
	s_add_u32 s34, s34, 0x100080
	v_mfma_f32_16x16x32_bf16 v[132:135], v[124:127], v[180:183], v[132:135]
	v_mfma_f32_16x16x32_bf16 v[128:131], v[140:143], v[180:183], v[128:131]
	v_lshl_add_u64 v[250:251], v[220:221], 0, s[14:15]
	v_mfma_f32_16x16x32_bf16 v[108:111], v[124:127], v[200:203], v[108:111]
	v_mfma_f32_16x16x32_bf16 v[104:107], v[140:143], v[200:203], v[104:107]
	s_addc_u32 s35, s35, 0
	v_mfma_f32_16x16x32_bf16 v[92:95], v[124:127], v[208:211], v[92:95]
	v_mfma_f32_16x16x32_bf16 v[88:91], v[140:143], v[208:211], v[88:91]
	v_lshl_add_u64 v[252:253], s[34:35], 0, v[154:155]
	v_mfma_f32_16x16x32_bf16 v[76:79], v[124:127], v[216:219], v[76:79]
	v_mfma_f32_16x16x32_bf16 v[72:75], v[140:143], v[216:219], v[72:75]
	v_lshl_add_u64 v[244:245], s[34:35], 0, v[158:159]
	v_mfma_f32_16x16x32_bf16 v[120:123], v[144:147], v[176:179], v[120:123]
	v_mfma_f32_16x16x32_bf16 v[116:119], v[168:171], v[176:179], v[116:119]
	v_lshl_add_u64 v[246:247], v[222:223], 0, s[14:15]
	v_mfma_f32_16x16x32_bf16 v[100:103], v[144:147], v[184:187], v[100:103]
	v_mfma_f32_16x16x32_bf16 v[96:99], v[168:171], v[184:187], v[96:99]
	v_lshl_add_u64 v[188:189], v[224:225], 0, s[14:15]
	v_mfma_f32_16x16x32_bf16 v[84:87], v[144:147], v[204:207], v[84:87]
	v_mfma_f32_16x16x32_bf16 v[80:83], v[168:171], v[204:207], v[80:83]
	v_mfma_f32_16x16x32_bf16 v[68:71], v[144:147], v[212:215], v[68:71]
	v_mfma_f32_16x16x32_bf16 v[64:67], v[168:171], v[212:215], v[64:67]
	v_mfma_f32_16x16x32_bf16 v[120:123], v[148:151], v[180:183], v[120:123]
	v_mfma_f32_16x16x32_bf16 v[116:119], v[172:175], v[180:183], v[116:119]
	v_mfma_f32_16x16x32_bf16 v[100:103], v[148:151], v[200:203], v[100:103]
	v_mfma_f32_16x16x32_bf16 v[96:99], v[172:175], v[200:203], v[96:99]
	v_mfma_f32_16x16x32_bf16 v[84:87], v[148:151], v[208:211], v[84:87]
	v_mfma_f32_16x16x32_bf16 v[80:83], v[172:175], v[208:211], v[80:83]
	v_mfma_f32_16x16x32_bf16 v[68:71], v[148:151], v[216:219], v[68:71]
	v_mfma_f32_16x16x32_bf16 v[64:67], v[172:175], v[216:219], v[64:67]
	s_barrier
	ds_read_b128 v[176:179], v195 offset:49152
	ds_read_b128 v[180:183], v195 offset:50176
	ds_read_b128 v[184:187], v195 offset:51200
	ds_read_b128 v[200:203], v195 offset:52224
	ds_read_b128 v[204:207], v195 offset:53248
	ds_read_b128 v[208:211], v195 offset:54272
	ds_read_b128 v[212:215], v195 offset:55296
	ds_read_b128 v[216:219], v195 offset:56320
	s_mov_b32 m0, s36
	s_nop 0
	global_load_lds_dwordx4 v[248:249], off
	s_add_i32 m0, s36, 0x2000
	s_add_i32 s36, s60, s41
	global_load_lds_dwordx4 v[250:251], off
	s_mov_b32 m0, s36
	s_nop 0
	global_load_lds_dwordx4 v[252:253], off
	s_add_i32 m0, s36, 0x2000
	s_nop 0
	global_load_lds_dwordx4 v[244:245], off
	s_mov_b32 m0, s46
	s_nop 0
	global_load_lds_dwordx4 v[246:247], off
	s_mov_b32 m0, s47
	s_nop 0
	global_load_lds_dwordx4 v[188:189], off
	s_waitcnt vmcnt(8)
	s_waitcnt lgkmcnt(0)
	s_barrier
	s_waitcnt lgkmcnt(0)
	v_mfma_f32_16x16x32_bf16 v[60:63], v[112:115], v[176:179], v[60:63]
	v_mfma_f32_16x16x32_bf16 v[56:59], v[136:139], v[176:179], v[56:59]
	v_mfma_f32_16x16x32_bf16 v[44:47], v[112:115], v[184:187], v[44:47]
	v_mfma_f32_16x16x32_bf16 v[40:43], v[136:139], v[184:187], v[40:43]
	v_mfma_f32_16x16x32_bf16 v[28:31], v[112:115], v[204:207], v[28:31]
	v_mfma_f32_16x16x32_bf16 v[24:27], v[136:139], v[204:207], v[24:27]
	v_mfma_f32_16x16x32_bf16 v[12:15], v[112:115], v[212:215], v[12:15]
	v_mfma_f32_16x16x32_bf16 v[8:11], v[136:139], v[212:215], v[8:11]
	v_mfma_f32_16x16x32_bf16 v[60:63], v[124:127], v[180:183], v[60:63]
	v_mfma_f32_16x16x32_bf16 v[56:59], v[140:143], v[180:183], v[56:59]
	v_mfma_f32_16x16x32_bf16 v[44:47], v[124:127], v[200:203], v[44:47]
	v_mfma_f32_16x16x32_bf16 v[40:43], v[140:143], v[200:203], v[40:43]
	v_mfma_f32_16x16x32_bf16 v[28:31], v[124:127], v[208:211], v[28:31]
	v_mfma_f32_16x16x32_bf16 v[24:27], v[140:143], v[208:211], v[24:27]
	v_mfma_f32_16x16x32_bf16 v[12:15], v[124:127], v[216:219], v[12:15]
	v_mfma_f32_16x16x32_bf16 v[8:11], v[140:143], v[216:219], v[8:11]
	v_mfma_f32_16x16x32_bf16 v[52:55], v[144:147], v[176:179], v[52:55]
	v_mfma_f32_16x16x32_bf16 v[48:51], v[168:171], v[176:179], v[48:51]
	v_mfma_f32_16x16x32_bf16 v[36:39], v[144:147], v[184:187], v[36:39]
	v_mfma_f32_16x16x32_bf16 v[32:35], v[168:171], v[184:187], v[32:35]
	v_mfma_f32_16x16x32_bf16 v[20:23], v[144:147], v[204:207], v[20:23]
	v_mfma_f32_16x16x32_bf16 v[16:19], v[168:171], v[204:207], v[16:19]
	v_mfma_f32_16x16x32_bf16 v[4:7], v[144:147], v[212:215], v[4:7]
	v_mfma_f32_16x16x32_bf16 v[0:3], v[168:171], v[212:215], v[0:3]
	v_mfma_f32_16x16x32_bf16 v[52:55], v[148:151], v[180:183], v[52:55]
	v_mfma_f32_16x16x32_bf16 v[48:51], v[172:175], v[180:183], v[48:51]
	v_mfma_f32_16x16x32_bf16 v[36:39], v[148:151], v[200:203], v[36:39]
	v_mfma_f32_16x16x32_bf16 v[32:35], v[172:175], v[200:203], v[32:35]
	v_mfma_f32_16x16x32_bf16 v[20:23], v[148:151], v[208:211], v[20:23]
	v_mfma_f32_16x16x32_bf16 v[16:19], v[172:175], v[208:211], v[16:19]
	v_mfma_f32_16x16x32_bf16 v[4:7], v[148:151], v[216:219], v[4:7]
	v_mfma_f32_16x16x32_bf16 v[0:3], v[172:175], v[216:219], v[0:3]
	s_barrier
	s_add_i32 s58, s58, 2
	s_add_u32 s56, s56, 0x100
	s_addc_u32 s57, s57, 0
	s_add_u32 s30, s30, 0x100
	s_addc_u32 s31, s31, 0
	s_cmp_gt_u32 s58, 61
	s_cbranch_scc0 .LBB0_451
	s_setprio 0
	s_and_b64 vcc, exec, s[16:17]
	s_cbranch_vccz .LBB0_454
	s_barrier

.Lsp_skip4:
.LBB0_550:
	ds_read_b128 v[144:147], v161
	ds_read_b128 v[148:151], v161 offset:1024
	ds_read_b128 v[170:173], v161 offset:2048
	ds_read_b128 v[174:177], v161 offset:3072
	ds_read_b128 v[178:181], v163
	ds_read_b128 v[182:185], v163 offset:1024
	ds_read_b128 v[186:189], v163 offset:2048
	ds_read_b128 v[190:193], v163 offset:3072
	ds_read_b128 v[194:197], v166
	ds_read_b128 v[198:201], v166 offset:1024
	ds_read_b128 v[202:205], v166 offset:2048
	ds_read_b128 v[206:209], v166 offset:3072
	ds_read_b128 v[210:213], v166 offset:4096
	ds_read_b128 v[214:217], v166 offset:5120
	ds_read_b128 v[218:221], v166 offset:6144
	ds_read_b128 v[222:225], v166 offset:7168
	s_add_u32 s6, s4, 0xfff80080
	s_addc_u32 s7, s5, -1
	s_cmp_eq_u32 s64, 28
	s_cselect_b32 s39, s1, s7
	s_cselect_b32 s38, s31, s6
	s_cselect_b32 s7, s29, s63
	s_cselect_b32 s6, s61, s62
	v_lshl_add_u64 v[152:153], s[4:5], 0, v[138:139]
	s_add_i32 m0, s45, 0xc000
	s_nop 0
	global_load_lds_dwordx4 v[152:153], off
	v_lshl_add_u64 v[152:153], s[4:5], 0, v[136:137]
	s_add_i32 m0, s45, 0xe000
	s_nop 0
	global_load_lds_dwordx4 v[152:153], off
	s_waitcnt vmcnt(8)
	s_waitcnt lgkmcnt(0)
	s_barrier
	s_waitcnt lgkmcnt(0)
	v_mfma_i32_16x16x64_i8 v[124:127], v[144:147], v[194:197], v[124:127]
	v_mfma_i32_16x16x64_i8 v[120:123], v[170:173], v[194:197], v[120:123]
	v_mfma_i32_16x16x64_i8 v[108:111], v[144:147], v[202:205], v[108:111]
	v_mfma_i32_16x16x64_i8 v[104:107], v[170:173], v[202:205], v[104:107]
	s_add_i32 s65, s53, s44
	v_mfma_i32_16x16x64_i8 v[92:95], v[144:147], v[210:213], v[92:95]
	v_mfma_i32_16x16x64_i8 v[88:91], v[170:173], v[210:213], v[88:91]
	v_lshl_add_u64 v[152:153], s[6:7], 0, v[130:131]
	v_mfma_i32_16x16x64_i8 v[76:79], v[144:147], v[218:221], v[76:79]
	v_mfma_i32_16x16x64_i8 v[72:75], v[170:173], v[218:221], v[72:75]
	s_add_u32 s66, s6, 0x80000
	v_mfma_i32_16x16x64_i8 v[124:127], v[148:151], v[198:201], v[124:127]
	v_mfma_i32_16x16x64_i8 v[120:123], v[174:177], v[198:201], v[120:123]
	v_lshl_add_u64 v[164:165], s[6:7], 0, v[134:135]
	v_mfma_i32_16x16x64_i8 v[108:111], v[148:151], v[206:209], v[108:111]
	v_mfma_i32_16x16x64_i8 v[104:107], v[174:177], v[206:209], v[104:107]
	s_addc_u32 s67, s7, 0
	v_mfma_i32_16x16x64_i8 v[92:95], v[148:151], v[214:217], v[92:95]
	v_mfma_i32_16x16x64_i8 v[88:91], v[174:177], v[214:217], v[88:91]
	v_lshl_add_u64 v[248:249], s[66:67], 0, v[130:131]
	v_mfma_i32_16x16x64_i8 v[76:79], v[148:151], v[222:225], v[76:79]
	v_mfma_i32_16x16x64_i8 v[72:75], v[174:177], v[222:225], v[72:75]
	v_lshl_add_u64 v[228:229], s[38:39], 0, v[132:133]
	v_mfma_i32_16x16x64_i8 v[116:119], v[178:181], v[194:197], v[116:119]
	v_mfma_i32_16x16x64_i8 v[112:115], v[186:189], v[194:197], v[112:115]
	v_lshl_add_u64 v[250:251], s[66:67], 0, v[134:135]
	v_mfma_i32_16x16x64_i8 v[100:103], v[178:181], v[202:205], v[100:103]
	v_mfma_i32_16x16x64_i8 v[96:99], v[186:189], v[202:205], v[96:99]
	v_lshl_add_u64 v[226:227], s[38:39], 0, v[128:129]
	v_mfma_i32_16x16x64_i8 v[84:87], v[178:181], v[210:213], v[84:87]
	v_mfma_i32_16x16x64_i8 v[80:83], v[186:189], v[210:213], v[80:83]
	v_mfma_i32_16x16x64_i8 v[68:71], v[178:181], v[218:221], v[68:71]
	v_mfma_i32_16x16x64_i8 v[64:67], v[186:189], v[218:221], v[64:67]
	v_mfma_i32_16x16x64_i8 v[116:119], v[182:185], v[198:201], v[116:119]
	v_mfma_i32_16x16x64_i8 v[112:115], v[190:193], v[198:201], v[112:115]
	v_mfma_i32_16x16x64_i8 v[100:103], v[182:185], v[206:209], v[100:103]
	v_mfma_i32_16x16x64_i8 v[96:99], v[190:193], v[206:209], v[96:99]
	v_mfma_i32_16x16x64_i8 v[84:87], v[182:185], v[214:217], v[84:87]
	v_mfma_i32_16x16x64_i8 v[80:83], v[190:193], v[214:217], v[80:83]
	v_mfma_i32_16x16x64_i8 v[68:71], v[182:185], v[222:225], v[68:71]
	v_mfma_i32_16x16x64_i8 v[64:67], v[190:193], v[222:225], v[64:67]
	s_barrier
	ds_read_b128 v[194:197], v166 offset:16384
	ds_read_b128 v[198:201], v166 offset:17408
	ds_read_b128 v[202:205], v166 offset:18432
	ds_read_b128 v[206:209], v166 offset:19456
	ds_read_b128 v[210:213], v166 offset:20480
	ds_read_b128 v[214:217], v166 offset:21504
	ds_read_b128 v[218:221], v166 offset:22528
	ds_read_b128 v[222:225], v166 offset:23552
	s_mov_b32 m0, s65
	s_nop 0
	global_load_lds_dwordx4 v[152:153], off
	s_add_i32 m0, s65, 0x2000
	s_add_i32 s65, s54, s44
	global_load_lds_dwordx4 v[164:165], off
	s_mov_b32 m0, s65
	s_nop 0
	global_load_lds_dwordx4 v[248:249], off
	s_add_i32 m0, s65, 0x2000
	s_nop 0
	global_load_lds_dwordx4 v[250:251], off
	s_mov_b32 m0, s45
	s_nop 0
	global_load_lds_dwordx4 v[226:227], off
	s_mov_b32 m0, s46
	s_nop 0
	global_load_lds_dwordx4 v[228:229], off
	s_waitcnt vmcnt(8)
	s_waitcnt lgkmcnt(0)
	s_barrier
	s_waitcnt lgkmcnt(0)
	v_mfma_i32_16x16x64_i8 v[60:63], v[144:147], v[194:197], v[60:63]
	v_mfma_i32_16x16x64_i8 v[56:59], v[170:173], v[194:197], v[56:59]
	v_mfma_i32_16x16x64_i8 v[44:47], v[144:147], v[202:205], v[44:47]
	v_mfma_i32_16x16x64_i8 v[40:43], v[170:173], v[202:205], v[40:43]
	s_add_i32 s65, 0, 0x18000
	v_mfma_i32_16x16x64_i8 v[28:31], v[144:147], v[210:213], v[28:31]
	v_mfma_i32_16x16x64_i8 v[24:27], v[170:173], v[210:213], v[24:27]
	v_add_u32_e32 v154, s65, v157
	v_mfma_i32_16x16x64_i8 v[12:15], v[144:147], v[218:221], v[12:15]
	v_mfma_i32_16x16x64_i8 v[8:11], v[170:173], v[218:221], v[8:11]
	s_add_i32 s66, 0, 0x1c000
	v_mfma_i32_16x16x64_i8 v[60:63], v[148:151], v[198:201], v[60:63]
	v_mfma_i32_16x16x64_i8 v[56:59], v[174:177], v[198:201], v[56:59]
	s_add_u32 s38, s38, 0x80000
	v_mfma_i32_16x16x64_i8 v[44:47], v[148:151], v[206:209], v[44:47]
	v_mfma_i32_16x16x64_i8 v[40:43], v[174:177], v[206:209], v[40:43]
	s_addc_u32 s39, s39, 0
	v_mfma_i32_16x16x64_i8 v[28:31], v[148:151], v[214:217], v[28:31]
	v_mfma_i32_16x16x64_i8 v[24:27], v[174:177], v[214:217], v[24:27]
	v_lshl_add_u64 v[248:249], s[38:39], 0, v[128:129]
	v_mfma_i32_16x16x64_i8 v[12:15], v[148:151], v[222:225], v[12:15]
	v_mfma_i32_16x16x64_i8 v[8:11], v[174:177], v[222:225], v[8:11]
	v_lshl_add_u64 v[230:231], s[38:39], 0, v[132:133]
	v_mfma_i32_16x16x64_i8 v[52:55], v[178:181], v[194:197], v[52:55]
	v_mfma_i32_16x16x64_i8 v[48:51], v[186:189], v[194:197], v[48:51]
	v_mfma_i32_16x16x64_i8 v[36:39], v[178:181], v[202:205], v[36:39]
	v_mfma_i32_16x16x64_i8 v[32:35], v[186:189], v[202:205], v[32:35]
	v_mfma_i32_16x16x64_i8 v[20:23], v[178:181], v[210:213], v[20:23]
	v_mfma_i32_16x16x64_i8 v[16:19], v[186:189], v[210:213], v[16:19]
	v_mfma_i32_16x16x64_i8 v[4:7], v[178:181], v[218:221], v[4:7]
	v_mfma_i32_16x16x64_i8 v[0:3], v[186:189], v[218:221], v[0:3]
	v_mfma_i32_16x16x64_i8 v[52:55], v[182:185], v[198:201], v[52:55]
	v_mfma_i32_16x16x64_i8 v[48:51], v[190:193], v[198:201], v[48:51]
	v_mfma_i32_16x16x64_i8 v[36:39], v[182:185], v[206:209], v[36:39]
	v_mfma_i32_16x16x64_i8 v[32:35], v[190:193], v[206:209], v[32:35]
	v_mfma_i32_16x16x64_i8 v[20:23], v[182:185], v[214:217], v[20:23]
	v_mfma_i32_16x16x64_i8 v[16:19], v[190:193], v[214:217], v[16:19]
	v_mfma_i32_16x16x64_i8 v[4:7], v[182:185], v[222:225], v[4:7]
	v_mfma_i32_16x16x64_i8 v[0:3], v[190:193], v[222:225], v[0:3]
	s_barrier
	ds_read_b128 v[194:197], v166 offset:32768
	ds_read_b128 v[198:201], v166 offset:33792
	ds_read_b128 v[202:205], v166 offset:34816
	ds_read_b128 v[206:209], v166 offset:35840
	ds_read_b128 v[210:213], v166 offset:36864
	ds_read_b128 v[214:217], v166 offset:37888
	ds_read_b128 v[218:221], v166 offset:38912
	ds_read_b128 v[222:225], v166 offset:39936
	ds_read_b128 v[144:147], v154
	ds_read_b128 v[148:151], v154 offset:1024
	ds_read_b128 v[170:173], v154 offset:2048
	ds_read_b128 v[174:177], v154 offset:3072
	v_add_u32_e32 v154, s66, v157
	ds_read_b128 v[178:181], v154
	ds_read_b128 v[182:185], v154 offset:1024
	ds_read_b128 v[186:189], v154 offset:2048
	ds_read_b128 v[190:193], v154 offset:3072
	s_mov_b32 m0, s47
	s_nop 0
	global_load_lds_dwordx4 v[248:249], off
	s_mov_b32 m0, s48
	s_nop 0
	global_load_lds_dwordx4 v[230:231], off
	s_waitcnt vmcnt(8)
	s_waitcnt lgkmcnt(0)
	s_barrier
	s_waitcnt lgkmcnt(0)
	v_mfma_i32_16x16x64_i8 v[124:127], v[144:147], v[194:197], v[124:127]
	v_mfma_i32_16x16x64_i8 v[120:123], v[170:173], v[194:197], v[120:123]
	v_mfma_i32_16x16x64_i8 v[108:111], v[144:147], v[202:205], v[108:111]
	v_mfma_i32_16x16x64_i8 v[104:107], v[170:173], v[202:205], v[104:107]
	s_add_i32 s38, s65, s44
	v_mfma_i32_16x16x64_i8 v[92:95], v[144:147], v[210:213], v[92:95]
	v_mfma_i32_16x16x64_i8 v[88:91], v[170:173], v[210:213], v[88:91]
	v_lshl_add_u64 v[248:249], v[152:153], 0, s[16:17]
	v_mfma_i32_16x16x64_i8 v[76:79], v[144:147], v[218:221], v[76:79]
	v_mfma_i32_16x16x64_i8 v[72:75], v[170:173], v[218:221], v[72:75]
	s_add_u32 s6, s6, 0x80080
	v_mfma_i32_16x16x64_i8 v[124:127], v[148:151], v[198:201], v[124:127]
	v_mfma_i32_16x16x64_i8 v[120:123], v[174:177], v[198:201], v[120:123]
	v_lshl_add_u64 v[250:251], v[164:165], 0, s[16:17]
	v_mfma_i32_16x16x64_i8 v[108:111], v[148:151], v[206:209], v[108:111]
	v_mfma_i32_16x16x64_i8 v[104:107], v[174:177], v[206:209], v[104:107]
	s_addc_u32 s7, s7, 0
	v_mfma_i32_16x16x64_i8 v[92:95], v[148:151], v[214:217], v[92:95]
	v_mfma_i32_16x16x64_i8 v[88:91], v[174:177], v[214:217], v[88:91]
	v_lshl_add_u64 v[252:253], s[6:7], 0, v[130:131]
	v_mfma_i32_16x16x64_i8 v[76:79], v[148:151], v[222:225], v[76:79]
	v_mfma_i32_16x16x64_i8 v[72:75], v[174:177], v[222:225], v[72:75]
	v_lshl_add_u64 v[152:153], s[6:7], 0, v[134:135]
	v_mfma_i32_16x16x64_i8 v[116:119], v[178:181], v[194:197], v[116:119]
	v_mfma_i32_16x16x64_i8 v[112:115], v[186:189], v[194:197], v[112:115]
	v_mfma_i32_16x16x64_i8 v[100:103], v[178:181], v[202:205], v[100:103]
	v_mfma_i32_16x16x64_i8 v[96:99], v[186:189], v[202:205], v[96:99]
	v_mfma_i32_16x16x64_i8 v[84:87], v[178:181], v[210:213], v[84:87]
	v_mfma_i32_16x16x64_i8 v[80:83], v[186:189], v[210:213], v[80:83]
	v_mfma_i32_16x16x64_i8 v[68:71], v[178:181], v[218:221], v[68:71]
	v_mfma_i32_16x16x64_i8 v[64:67], v[186:189], v[218:221], v[64:67]
	v_mfma_i32_16x16x64_i8 v[116:119], v[182:185], v[198:201], v[116:119]
	v_mfma_i32_16x16x64_i8 v[112:115], v[190:193], v[198:201], v[112:115]
	v_mfma_i32_16x16x64_i8 v[100:103], v[182:185], v[206:209], v[100:103]
	v_mfma_i32_16x16x64_i8 v[96:99], v[190:193], v[206:209], v[96:99]
	v_mfma_i32_16x16x64_i8 v[84:87], v[182:185], v[214:217], v[84:87]
	v_mfma_i32_16x16x64_i8 v[80:83], v[190:193], v[214:217], v[80:83]
	v_mfma_i32_16x16x64_i8 v[68:71], v[182:185], v[222:225], v[68:71]
	v_mfma_i32_16x16x64_i8 v[64:67], v[190:193], v[222:225], v[64:67]
	s_barrier
	ds_read_b128 v[194:197], v166 offset:49152
	ds_read_b128 v[198:201], v166 offset:50176
	ds_read_b128 v[202:205], v166 offset:51200
	ds_read_b128 v[206:209], v166 offset:52224
	ds_read_b128 v[210:213], v166 offset:53248
	ds_read_b128 v[214:217], v166 offset:54272
	ds_read_b128 v[218:221], v166 offset:55296
	ds_read_b128 v[222:225], v166 offset:56320
	s_mov_b32 m0, s38
	s_nop 0
	global_load_lds_dwordx4 v[248:249], off
	s_add_i32 m0, s38, 0x2000
	s_add_i32 s38, s66, s44
	global_load_lds_dwordx4 v[250:251], off
	s_mov_b32 m0, s38
	s_nop 0
	global_load_lds_dwordx4 v[252:253], off
	s_add_i32 m0, s38, 0x2000
	s_nop 0
	global_load_lds_dwordx4 v[152:153], off
	v_lshl_add_u64 v[152:153], v[226:227], 0, s[16:17]
	s_mov_b32 m0, s50
	s_nop 0
	global_load_lds_dwordx4 v[152:153], off
	v_lshl_add_u64 v[152:153], v[228:229], 0, s[16:17]
	s_mov_b32 m0, s51
	s_nop 0
	global_load_lds_dwordx4 v[152:153], off
	s_waitcnt vmcnt(8)
	s_waitcnt lgkmcnt(0)
	s_barrier
	s_waitcnt lgkmcnt(0)
	v_mfma_i32_16x16x64_i8 v[60:63], v[144:147], v[194:197], v[60:63]
	v_mfma_i32_16x16x64_i8 v[56:59], v[170:173], v[194:197], v[56:59]
	v_mfma_i32_16x16x64_i8 v[44:47], v[144:147], v[202:205], v[44:47]
	v_mfma_i32_16x16x64_i8 v[40:43], v[170:173], v[202:205], v[40:43]
	v_mfma_i32_16x16x64_i8 v[28:31], v[144:147], v[210:213], v[28:31]
	v_mfma_i32_16x16x64_i8 v[24:27], v[170:173], v[210:213], v[24:27]
	v_mfma_i32_16x16x64_i8 v[12:15], v[144:147], v[218:221], v[12:15]
	v_mfma_i32_16x16x64_i8 v[8:11], v[170:173], v[218:221], v[8:11]
	v_mfma_i32_16x16x64_i8 v[60:63], v[148:151], v[198:201], v[60:63]
	v_mfma_i32_16x16x64_i8 v[56:59], v[174:177], v[198:201], v[56:59]
	v_mfma_i32_16x16x64_i8 v[44:47], v[148:151], v[206:209], v[44:47]
	v_mfma_i32_16x16x64_i8 v[40:43], v[174:177], v[206:209], v[40:43]
	v_mfma_i32_16x16x64_i8 v[28:31], v[148:151], v[214:217], v[28:31]
	v_mfma_i32_16x16x64_i8 v[24:27], v[174:177], v[214:217], v[24:27]
	v_mfma_i32_16x16x64_i8 v[12:15], v[148:151], v[222:225], v[12:15]
	v_mfma_i32_16x16x64_i8 v[8:11], v[174:177], v[222:225], v[8:11]
	v_mfma_i32_16x16x64_i8 v[52:55], v[178:181], v[194:197], v[52:55]
	v_mfma_i32_16x16x64_i8 v[48:51], v[186:189], v[194:197], v[48:51]
	v_mfma_i32_16x16x64_i8 v[36:39], v[178:181], v[202:205], v[36:39]
	v_mfma_i32_16x16x64_i8 v[32:35], v[186:189], v[202:205], v[32:35]
	v_mfma_i32_16x16x64_i8 v[20:23], v[178:181], v[210:213], v[20:23]
	v_mfma_i32_16x16x64_i8 v[16:19], v[186:189], v[210:213], v[16:19]
	v_mfma_i32_16x16x64_i8 v[4:7], v[178:181], v[218:221], v[4:7]
	v_mfma_i32_16x16x64_i8 v[0:3], v[186:189], v[218:221], v[0:3]
	v_mfma_i32_16x16x64_i8 v[52:55], v[182:185], v[198:201], v[52:55]
	v_mfma_i32_16x16x64_i8 v[48:51], v[190:193], v[198:201], v[48:51]
	v_mfma_i32_16x16x64_i8 v[36:39], v[182:185], v[206:209], v[36:39]
	v_mfma_i32_16x16x64_i8 v[32:35], v[190:193], v[206:209], v[32:35]
	v_mfma_i32_16x16x64_i8 v[20:23], v[182:185], v[214:217], v[20:23]
	v_mfma_i32_16x16x64_i8 v[16:19], v[190:193], v[214:217], v[16:19]
	v_mfma_i32_16x16x64_i8 v[4:7], v[182:185], v[222:225], v[4:7]
	v_mfma_i32_16x16x64_i8 v[0:3], v[190:193], v[222:225], v[0:3]
	s_barrier
	s_add_i32 s64, s64, 2
	s_add_u32 s62, s62, 0x100
	s_addc_u32 s63, s63, 0
	s_add_u32 s4, s4, 0x100
	s_addc_u32 s5, s5, 0
	s_cmp_gt_u32 s64, 29
	s_cbranch_scc0 .LBB0_550
	s_setprio 0
	s_and_b64 vcc, exec, s[18:19]
	s_cbranch_vccz .LBB0_553
	s_barrier

.Lsp_skip5:
.LBB0_635:
	ds_read_b128 v[112:115], v193
	ds_read_b128 v[124:127], v193 offset:1024
	ds_read_b128 v[136:139], v193 offset:2048
	ds_read_b128 v[140:143], v193 offset:3072
	ds_read_b128 v[144:147], v194
	ds_read_b128 v[148:151], v194 offset:1024
	ds_read_b128 v[168:171], v194 offset:2048
	ds_read_b128 v[172:175], v194 offset:3072
	ds_read_b128 v[176:179], v195
	ds_read_b128 v[180:183], v195 offset:1024
	ds_read_b128 v[184:187], v195 offset:2048
	ds_read_b128 v[200:203], v195 offset:3072
	ds_read_b128 v[204:207], v195 offset:4096
	ds_read_b128 v[208:211], v195 offset:5120
	ds_read_b128 v[212:215], v195 offset:6144
	ds_read_b128 v[216:219], v195 offset:7168
	s_add_u32 s34, s30, 0xffbf8080
	s_addc_u32 s35, s31, -1
	s_cmpk_eq_i32 s58, 0xfc
	s_cselect_b32 s37, s21, s35
	s_cselect_b32 s36, s27, s34
	s_cselect_b32 s35, s19, s57
	s_cselect_b32 s34, s55, s56
	v_lshl_add_u64 v[188:189], s[30:31], 0, v[162:163]
	s_add_i32 m0, s29, 0xc000
	s_nop 0
	global_load_lds_dwordx4 v[188:189], off
	v_lshl_add_u64 v[188:189], s[30:31], 0, v[160:161]
	s_add_i32 m0, s29, 0xe000
	s_nop 0
	global_load_lds_dwordx4 v[188:189], off
	s_waitcnt vmcnt(8)
	s_waitcnt lgkmcnt(0)
	s_barrier
	s_waitcnt lgkmcnt(0)
	v_mfma_f32_16x16x32_bf16 v[132:135], v[112:115], v[176:179], v[132:135]
	v_mfma_f32_16x16x32_bf16 v[128:131], v[136:139], v[176:179], v[128:131]
	v_mfma_f32_16x16x32_bf16 v[108:111], v[112:115], v[184:187], v[108:111]
	v_mfma_f32_16x16x32_bf16 v[104:107], v[136:139], v[184:187], v[104:107]
	s_add_i32 s59, s50, s41
	v_mfma_f32_16x16x32_bf16 v[92:95], v[112:115], v[204:207], v[92:95]
	v_mfma_f32_16x16x32_bf16 v[88:91], v[136:139], v[204:207], v[88:91]
	v_lshl_add_u64 v[188:189], s[34:35], 0, v[154:155]
	v_mfma_f32_16x16x32_bf16 v[76:79], v[112:115], v[212:215], v[76:79]
	v_mfma_f32_16x16x32_bf16 v[72:75], v[136:139], v[212:215], v[72:75]
	s_add_u32 s60, s34, 0x400000
	v_mfma_f32_16x16x32_bf16 v[132:135], v[124:127], v[180:183], v[132:135]
	v_mfma_f32_16x16x32_bf16 v[128:131], v[140:143], v[180:183], v[128:131]
	v_lshl_add_u64 v[220:221], s[34:35], 0, v[158:159]
	v_mfma_f32_16x16x32_bf16 v[108:111], v[124:127], v[200:203], v[108:111]
	v_mfma_f32_16x16x32_bf16 v[104:107], v[140:143], v[200:203], v[104:107]
	s_addc_u32 s61, s35, 0
	v_mfma_f32_16x16x32_bf16 v[92:95], v[124:127], v[208:211], v[92:95]
	v_mfma_f32_16x16x32_bf16 v[88:91], v[140:143], v[208:211], v[88:91]
	v_lshl_add_u64 v[248:249], s[60:61], 0, v[154:155]
	v_mfma_f32_16x16x32_bf16 v[76:79], v[124:127], v[216:219], v[76:79]
	v_mfma_f32_16x16x32_bf16 v[72:75], v[140:143], v[216:219], v[72:75]
	v_lshl_add_u64 v[224:225], s[36:37], 0, v[156:157]
	v_mfma_f32_16x16x32_bf16 v[120:123], v[144:147], v[176:179], v[120:123]
	v_mfma_f32_16x16x32_bf16 v[116:119], v[168:171], v[176:179], v[116:119]
	v_lshl_add_u64 v[250:251], s[60:61], 0, v[158:159]
	v_mfma_f32_16x16x32_bf16 v[100:103], v[144:147], v[184:187], v[100:103]
	v_mfma_f32_16x16x32_bf16 v[96:99], v[168:171], v[184:187], v[96:99]
	v_lshl_add_u64 v[222:223], s[36:37], 0, v[152:153]
	v_mfma_f32_16x16x32_bf16 v[84:87], v[144:147], v[204:207], v[84:87]
	v_mfma_f32_16x16x32_bf16 v[80:83], v[168:171], v[204:207], v[80:83]
	v_mfma_f32_16x16x32_bf16 v[68:71], v[144:147], v[212:215], v[68:71]
	v_mfma_f32_16x16x32_bf16 v[64:67], v[168:171], v[212:215], v[64:67]
	v_mfma_f32_16x16x32_bf16 v[120:123], v[148:151], v[180:183], v[120:123]
	v_mfma_f32_16x16x32_bf16 v[116:119], v[172:175], v[180:183], v[116:119]
	v_mfma_f32_16x16x32_bf16 v[100:103], v[148:151], v[200:203], v[100:103]
	v_mfma_f32_16x16x32_bf16 v[96:99], v[172:175], v[200:203], v[96:99]
	v_mfma_f32_16x16x32_bf16 v[84:87], v[148:151], v[208:211], v[84:87]
	v_mfma_f32_16x16x32_bf16 v[80:83], v[172:175], v[208:211], v[80:83]
	v_mfma_f32_16x16x32_bf16 v[68:71], v[148:151], v[216:219], v[68:71]
	v_mfma_f32_16x16x32_bf16 v[64:67], v[172:175], v[216:219], v[64:67]
	s_barrier
	ds_read_b128 v[176:179], v195 offset:16384
	ds_read_b128 v[180:183], v195 offset:17408
	ds_read_b128 v[184:187], v195 offset:18432
	ds_read_b128 v[200:203], v195 offset:19456
	ds_read_b128 v[204:207], v195 offset:20480
	ds_read_b128 v[208:211], v195 offset:21504
	ds_read_b128 v[212:215], v195 offset:22528
	ds_read_b128 v[216:219], v195 offset:23552
	s_mov_b32 m0, s59
	s_nop 0
	global_load_lds_dwordx4 v[188:189], off
	s_add_i32 m0, s59, 0x2000
	s_add_i32 s59, s51, s41
	global_load_lds_dwordx4 v[220:221], off
	s_mov_b32 m0, s59
	s_nop 0
	global_load_lds_dwordx4 v[248:249], off
	s_add_i32 m0, s59, 0x2000
	s_nop 0
	global_load_lds_dwordx4 v[250:251], off
	s_mov_b32 m0, s29
	s_nop 0
	global_load_lds_dwordx4 v[222:223], off
	s_mov_b32 m0, s42
	s_nop 0
	global_load_lds_dwordx4 v[224:225], off
	s_waitcnt vmcnt(8)
	s_waitcnt lgkmcnt(0)
	s_barrier
	s_waitcnt lgkmcnt(0)
	v_mfma_f32_16x16x32_bf16 v[60:63], v[112:115], v[176:179], v[60:63]
	v_mfma_f32_16x16x32_bf16 v[56:59], v[136:139], v[176:179], v[56:59]
	v_mfma_f32_16x16x32_bf16 v[44:47], v[112:115], v[184:187], v[44:47]
	v_mfma_f32_16x16x32_bf16 v[40:43], v[136:139], v[184:187], v[40:43]
	s_add_i32 s59, 0, 0x18000
	v_mfma_f32_16x16x32_bf16 v[28:31], v[112:115], v[204:207], v[28:31]
	v_mfma_f32_16x16x32_bf16 v[24:27], v[136:139], v[204:207], v[24:27]
	s_add_i32 s60, 0, 0x1c000
	v_mfma_f32_16x16x32_bf16 v[12:15], v[112:115], v[212:215], v[12:15]
	v_mfma_f32_16x16x32_bf16 v[8:11], v[136:139], v[212:215], v[8:11]
	s_add_u32 s36, s36, 0x408000
	v_mfma_f32_16x16x32_bf16 v[60:63], v[124:127], v[180:183], v[60:63]
	v_mfma_f32_16x16x32_bf16 v[56:59], v[140:143], v[180:183], v[56:59]
	s_addc_u32 s37, s37, 0
	v_mfma_f32_16x16x32_bf16 v[44:47], v[124:127], v[200:203], v[44:47]
	v_mfma_f32_16x16x32_bf16 v[40:43], v[140:143], v[200:203], v[40:43]
	v_lshl_add_u64 v[248:249], s[36:37], 0, v[152:153]
	v_mfma_f32_16x16x32_bf16 v[28:31], v[124:127], v[208:211], v[28:31]
	v_mfma_f32_16x16x32_bf16 v[24:27], v[140:143], v[208:211], v[24:27]
	v_lshl_add_u64 v[226:227], s[36:37], 0, v[156:157]
	v_mfma_f32_16x16x32_bf16 v[12:15], v[124:127], v[216:219], v[12:15]
	v_mfma_f32_16x16x32_bf16 v[8:11], v[140:143], v[216:219], v[8:11]
	v_mfma_f32_16x16x32_bf16 v[52:55], v[144:147], v[176:179], v[52:55]
	v_mfma_f32_16x16x32_bf16 v[48:51], v[168:171], v[176:179], v[48:51]
	v_mfma_f32_16x16x32_bf16 v[36:39], v[144:147], v[184:187], v[36:39]
	v_mfma_f32_16x16x32_bf16 v[32:35], v[168:171], v[184:187], v[32:35]
	v_mfma_f32_16x16x32_bf16 v[20:23], v[144:147], v[204:207], v[20:23]
	v_mfma_f32_16x16x32_bf16 v[16:19], v[168:171], v[204:207], v[16:19]
	v_mfma_f32_16x16x32_bf16 v[4:7], v[144:147], v[212:215], v[4:7]
	v_mfma_f32_16x16x32_bf16 v[0:3], v[168:171], v[212:215], v[0:3]
	v_mfma_f32_16x16x32_bf16 v[52:55], v[148:151], v[180:183], v[52:55]
	v_mfma_f32_16x16x32_bf16 v[48:51], v[172:175], v[180:183], v[48:51]
	v_mfma_f32_16x16x32_bf16 v[36:39], v[148:151], v[200:203], v[36:39]
	v_mfma_f32_16x16x32_bf16 v[32:35], v[172:175], v[200:203], v[32:35]
	v_mfma_f32_16x16x32_bf16 v[20:23], v[148:151], v[208:211], v[20:23]
	v_mfma_f32_16x16x32_bf16 v[16:19], v[172:175], v[208:211], v[16:19]
	v_mfma_f32_16x16x32_bf16 v[4:7], v[148:151], v[216:219], v[4:7]
	v_mfma_f32_16x16x32_bf16 v[0:3], v[172:175], v[216:219], v[0:3]
	s_barrier
	ds_read_b128 v[176:179], v195 offset:32768
	ds_read_b128 v[180:183], v195 offset:33792
	ds_read_b128 v[184:187], v195 offset:34816
	ds_read_b128 v[200:203], v195 offset:35840
	ds_read_b128 v[204:207], v195 offset:36864
	ds_read_b128 v[208:211], v195 offset:37888
	ds_read_b128 v[212:215], v195 offset:38912
	ds_read_b128 v[216:219], v195 offset:39936
	v_add_u32_e32 v140, s59, v191
	v_add_u32_e32 v172, s60, v191
	ds_read_b128 v[112:115], v140
	ds_read_b128 v[124:127], v140 offset:1024
	ds_read_b128 v[136:139], v140 offset:2048
	ds_read_b128 v[140:143], v140 offset:3072
	ds_read_b128 v[144:147], v172
	ds_read_b128 v[148:151], v172 offset:1024
	ds_read_b128 v[168:171], v172 offset:2048
	ds_read_b128 v[172:175], v172 offset:3072
	s_mov_b32 m0, s43
	s_nop 0
	global_load_lds_dwordx4 v[248:249], off
	s_mov_b32 m0, s44
	s_nop 0
	global_load_lds_dwordx4 v[226:227], off
	s_waitcnt vmcnt(8)
	s_waitcnt lgkmcnt(0)
	s_barrier
	s_waitcnt lgkmcnt(0)
	v_mfma_f32_16x16x32_bf16 v[132:135], v[112:115], v[176:179], v[132:135]
	v_mfma_f32_16x16x32_bf16 v[128:131], v[136:139], v[176:179], v[128:131]
	v_mfma_f32_16x16x32_bf16 v[108:111], v[112:115], v[184:187], v[108:111]
	v_mfma_f32_16x16x32_bf16 v[104:107], v[136:139], v[184:187], v[104:107]
	s_add_i32 s36, s59, s41
	v_mfma_f32_16x16x32_bf16 v[92:95], v[112:115], v[204:207], v[92:95]
	v_mfma_f32_16x16x32_bf16 v[88:91], v[136:139], v[204:207], v[88:91]
	v_lshl_add_u64 v[248:249], v[188:189], 0, s[14:15]
	v_mfma_f32_16x16x32_bf16 v[76:79], v[112:115], v[212:215], v[76:79]
	v_mfma_f32_16x16x32_bf16 v[72:75], v[136:139], v[212:215], v[72:75]
	s_add_u32 s34, s34, 0x400080
	v_mfma_f32_16x16x32_bf16 v[132:135], v[124:127], v[180:183], v[132:135]
	v_mfma_f32_16x16x32_bf16 v[128:131], v[140:143], v[180:183], v[128:131]
	v_lshl_add_u64 v[250:251], v[220:221], 0, s[14:15]
	v_mfma_f32_16x16x32_bf16 v[108:111], v[124:127], v[200:203], v[108:111]
	v_mfma_f32_16x16x32_bf16 v[104:107], v[140:143], v[200:203], v[104:107]
	s_addc_u32 s35, s35, 0
	v_mfma_f32_16x16x32_bf16 v[92:95], v[124:127], v[208:211], v[92:95]
	v_mfma_f32_16x16x32_bf16 v[88:91], v[140:143], v[208:211], v[88:91]
	v_lshl_add_u64 v[252:253], s[34:35], 0, v[154:155]
	v_mfma_f32_16x16x32_bf16 v[76:79], v[124:127], v[216:219], v[76:79]
	v_mfma_f32_16x16x32_bf16 v[72:75], v[140:143], v[216:219], v[72:75]
	v_lshl_add_u64 v[244:245], s[34:35], 0, v[158:159]
	v_mfma_f32_16x16x32_bf16 v[120:123], v[144:147], v[176:179], v[120:123]
	v_mfma_f32_16x16x32_bf16 v[116:119], v[168:171], v[176:179], v[116:119]
	v_lshl_add_u64 v[246:247], v[222:223], 0, s[14:15]
	v_mfma_f32_16x16x32_bf16 v[100:103], v[144:147], v[184:187], v[100:103]
	v_mfma_f32_16x16x32_bf16 v[96:99], v[168:171], v[184:187], v[96:99]
	v_lshl_add_u64 v[188:189], v[224:225], 0, s[14:15]
	v_mfma_f32_16x16x32_bf16 v[84:87], v[144:147], v[204:207], v[84:87]
	v_mfma_f32_16x16x32_bf16 v[80:83], v[168:171], v[204:207], v[80:83]
	v_mfma_f32_16x16x32_bf16 v[68:71], v[144:147], v[212:215], v[68:71]
	v_mfma_f32_16x16x32_bf16 v[64:67], v[168:171], v[212:215], v[64:67]
	v_mfma_f32_16x16x32_bf16 v[120:123], v[148:151], v[180:183], v[120:123]
	v_mfma_f32_16x16x32_bf16 v[116:119], v[172:175], v[180:183], v[116:119]
	v_mfma_f32_16x16x32_bf16 v[100:103], v[148:151], v[200:203], v[100:103]
	v_mfma_f32_16x16x32_bf16 v[96:99], v[172:175], v[200:203], v[96:99]
	v_mfma_f32_16x16x32_bf16 v[84:87], v[148:151], v[208:211], v[84:87]
	v_mfma_f32_16x16x32_bf16 v[80:83], v[172:175], v[208:211], v[80:83]
	v_mfma_f32_16x16x32_bf16 v[68:71], v[148:151], v[216:219], v[68:71]
	v_mfma_f32_16x16x32_bf16 v[64:67], v[172:175], v[216:219], v[64:67]
	s_barrier
	ds_read_b128 v[176:179], v195 offset:49152
	ds_read_b128 v[180:183], v195 offset:50176
	ds_read_b128 v[184:187], v195 offset:51200
	ds_read_b128 v[200:203], v195 offset:52224
	ds_read_b128 v[204:207], v195 offset:53248
	ds_read_b128 v[208:211], v195 offset:54272
	ds_read_b128 v[212:215], v195 offset:55296
	ds_read_b128 v[216:219], v195 offset:56320
	s_mov_b32 m0, s36
	s_nop 0
	global_load_lds_dwordx4 v[248:249], off
	s_add_i32 m0, s36, 0x2000
	s_add_i32 s36, s60, s41
	global_load_lds_dwordx4 v[250:251], off
	s_mov_b32 m0, s36
	s_nop 0
	global_load_lds_dwordx4 v[252:253], off
	s_add_i32 m0, s36, 0x2000
	s_nop 0
	global_load_lds_dwordx4 v[244:245], off
	s_mov_b32 m0, s46
	s_nop 0
	global_load_lds_dwordx4 v[246:247], off
	s_mov_b32 m0, s47
	s_nop 0
	global_load_lds_dwordx4 v[188:189], off
	s_waitcnt vmcnt(8)
	s_waitcnt lgkmcnt(0)
	s_barrier
	s_waitcnt lgkmcnt(0)
	v_mfma_f32_16x16x32_bf16 v[60:63], v[112:115], v[176:179], v[60:63]
	v_mfma_f32_16x16x32_bf16 v[56:59], v[136:139], v[176:179], v[56:59]
	v_mfma_f32_16x16x32_bf16 v[44:47], v[112:115], v[184:187], v[44:47]
	v_mfma_f32_16x16x32_bf16 v[40:43], v[136:139], v[184:187], v[40:43]
	v_mfma_f32_16x16x32_bf16 v[28:31], v[112:115], v[204:207], v[28:31]
	v_mfma_f32_16x16x32_bf16 v[24:27], v[136:139], v[204:207], v[24:27]
	v_mfma_f32_16x16x32_bf16 v[12:15], v[112:115], v[212:215], v[12:15]
	v_mfma_f32_16x16x32_bf16 v[8:11], v[136:139], v[212:215], v[8:11]
	v_mfma_f32_16x16x32_bf16 v[60:63], v[124:127], v[180:183], v[60:63]
	v_mfma_f32_16x16x32_bf16 v[56:59], v[140:143], v[180:183], v[56:59]
	v_mfma_f32_16x16x32_bf16 v[44:47], v[124:127], v[200:203], v[44:47]
	v_mfma_f32_16x16x32_bf16 v[40:43], v[140:143], v[200:203], v[40:43]
	v_mfma_f32_16x16x32_bf16 v[28:31], v[124:127], v[208:211], v[28:31]
	v_mfma_f32_16x16x32_bf16 v[24:27], v[140:143], v[208:211], v[24:27]
	v_mfma_f32_16x16x32_bf16 v[12:15], v[124:127], v[216:219], v[12:15]
	v_mfma_f32_16x16x32_bf16 v[8:11], v[140:143], v[216:219], v[8:11]
	v_mfma_f32_16x16x32_bf16 v[52:55], v[144:147], v[176:179], v[52:55]
	v_mfma_f32_16x16x32_bf16 v[48:51], v[168:171], v[176:179], v[48:51]
	v_mfma_f32_16x16x32_bf16 v[36:39], v[144:147], v[184:187], v[36:39]
	v_mfma_f32_16x16x32_bf16 v[32:35], v[168:171], v[184:187], v[32:35]
	v_mfma_f32_16x16x32_bf16 v[20:23], v[144:147], v[204:207], v[20:23]
	v_mfma_f32_16x16x32_bf16 v[16:19], v[168:171], v[204:207], v[16:19]
	v_mfma_f32_16x16x32_bf16 v[4:7], v[144:147], v[212:215], v[4:7]
	v_mfma_f32_16x16x32_bf16 v[0:3], v[168:171], v[212:215], v[0:3]
	v_mfma_f32_16x16x32_bf16 v[52:55], v[148:151], v[180:183], v[52:55]
	v_mfma_f32_16x16x32_bf16 v[48:51], v[172:175], v[180:183], v[48:51]
	v_mfma_f32_16x16x32_bf16 v[36:39], v[148:151], v[200:203], v[36:39]
	v_mfma_f32_16x16x32_bf16 v[32:35], v[172:175], v[200:203], v[32:35]
	v_mfma_f32_16x16x32_bf16 v[20:23], v[148:151], v[208:211], v[20:23]
	v_mfma_f32_16x16x32_bf16 v[16:19], v[172:175], v[208:211], v[16:19]
	v_mfma_f32_16x16x32_bf16 v[4:7], v[148:151], v[216:219], v[4:7]
	v_mfma_f32_16x16x32_bf16 v[0:3], v[172:175], v[216:219], v[0:3]
	s_barrier
	s_add_i32 s58, s58, 2
	s_add_u32 s56, s56, 0x100
	s_addc_u32 s57, s57, 0
	s_add_u32 s30, s30, 0x100
	s_addc_u32 s31, s31, 0
	s_cmpk_gt_u32 s58, 0xfd
	s_cbranch_scc0 .LBB0_635
	s_setprio 0
	s_and_b64 vcc, exec, s[16:17]
	s_cbranch_vccz .LBB0_638
	s_barrier

.Lsp_skip6:
.LBB0_726:
	ds_read_b128 v[144:147], v161
	ds_read_b128 v[148:151], v161 offset:1024
	ds_read_b128 v[168:171], v161 offset:2048
	ds_read_b128 v[172:175], v161 offset:3072
	ds_read_b128 v[176:179], v163
	ds_read_b128 v[180:183], v163 offset:1024
	ds_read_b128 v[184:187], v163 offset:2048
	ds_read_b128 v[188:191], v163 offset:3072
	ds_read_b128 v[192:195], v165
	ds_read_b128 v[196:199], v165 offset:1024
	ds_read_b128 v[200:203], v165 offset:2048
	ds_read_b128 v[204:207], v165 offset:3072
	ds_read_b128 v[208:211], v165 offset:4096
	ds_read_b128 v[212:215], v165 offset:5120
	ds_read_b128 v[216:219], v165 offset:6144
	ds_read_b128 v[220:223], v165 offset:7168
	s_add_u32 s6, s4, 0xfff80080
	s_addc_u32 s7, s5, -1
	s_cmp_eq_u32 s54, 28
	s_cselect_b32 s29, s1, s7
	s_cselect_b32 s28, s23, s6
	s_cselect_b32 s7, s21, s53
	s_cselect_b32 s6, s51, s52
	v_lshl_add_u64 v[152:153], s[4:5], 0, v[138:139]
	s_add_i32 m0, s38, 0xc000
	s_nop 0
	global_load_lds_dwordx4 v[152:153], off
	v_lshl_add_u64 v[152:153], s[4:5], 0, v[136:137]
	s_add_i32 m0, s38, 0xe000
	s_nop 0
	global_load_lds_dwordx4 v[152:153], off
	s_waitcnt vmcnt(8)
	s_waitcnt lgkmcnt(0)
	s_barrier
	s_waitcnt lgkmcnt(0)
	v_mfma_i32_16x16x64_i8 v[124:127], v[144:147], v[192:195], v[124:127]
	v_mfma_i32_16x16x64_i8 v[120:123], v[168:171], v[192:195], v[120:123]
	v_mfma_i32_16x16x64_i8 v[108:111], v[144:147], v[200:203], v[108:111]
	v_mfma_i32_16x16x64_i8 v[104:107], v[168:171], v[200:203], v[104:107]
	s_add_i32 s55, s46, s35
	v_mfma_i32_16x16x64_i8 v[92:95], v[144:147], v[208:211], v[92:95]
	v_mfma_i32_16x16x64_i8 v[88:91], v[168:171], v[208:211], v[88:91]
	v_lshl_add_u64 v[152:153], s[6:7], 0, v[132:133]
	v_mfma_i32_16x16x64_i8 v[76:79], v[144:147], v[216:219], v[76:79]
	v_mfma_i32_16x16x64_i8 v[72:75], v[168:171], v[216:219], v[72:75]
	s_add_u32 s56, s6, 0x80000
	v_mfma_i32_16x16x64_i8 v[124:127], v[148:151], v[196:199], v[124:127]
	v_mfma_i32_16x16x64_i8 v[120:123], v[172:175], v[196:199], v[120:123]
	v_lshl_add_u64 v[224:225], s[6:7], 0, v[128:129]
	v_mfma_i32_16x16x64_i8 v[108:111], v[148:151], v[204:207], v[108:111]
	v_mfma_i32_16x16x64_i8 v[104:107], v[172:175], v[204:207], v[104:107]
	s_addc_u32 s57, s7, 0
	v_mfma_i32_16x16x64_i8 v[92:95], v[148:151], v[212:215], v[92:95]
	v_mfma_i32_16x16x64_i8 v[88:91], v[172:175], v[212:215], v[88:91]
	v_lshl_add_u64 v[248:249], s[56:57], 0, v[132:133]
	v_mfma_i32_16x16x64_i8 v[76:79], v[148:151], v[220:223], v[76:79]
	v_mfma_i32_16x16x64_i8 v[72:75], v[172:175], v[220:223], v[72:75]
	v_lshl_add_u64 v[228:229], s[28:29], 0, v[130:131]
	v_mfma_i32_16x16x64_i8 v[116:119], v[176:179], v[192:195], v[116:119]
	v_mfma_i32_16x16x64_i8 v[112:115], v[184:187], v[192:195], v[112:115]
	v_lshl_add_u64 v[250:251], s[56:57], 0, v[128:129]
	v_mfma_i32_16x16x64_i8 v[100:103], v[176:179], v[200:203], v[100:103]
	v_mfma_i32_16x16x64_i8 v[96:99], v[184:187], v[200:203], v[96:99]
	v_lshl_add_u64 v[226:227], s[28:29], 0, v[134:135]
	v_mfma_i32_16x16x64_i8 v[84:87], v[176:179], v[208:211], v[84:87]
	v_mfma_i32_16x16x64_i8 v[80:83], v[184:187], v[208:211], v[80:83]
	v_mfma_i32_16x16x64_i8 v[68:71], v[176:179], v[216:219], v[68:71]
	v_mfma_i32_16x16x64_i8 v[64:67], v[184:187], v[216:219], v[64:67]
	v_mfma_i32_16x16x64_i8 v[116:119], v[180:183], v[196:199], v[116:119]
	v_mfma_i32_16x16x64_i8 v[112:115], v[188:191], v[196:199], v[112:115]
	v_mfma_i32_16x16x64_i8 v[100:103], v[180:183], v[204:207], v[100:103]
	v_mfma_i32_16x16x64_i8 v[96:99], v[188:191], v[204:207], v[96:99]
	v_mfma_i32_16x16x64_i8 v[84:87], v[180:183], v[212:215], v[84:87]
	v_mfma_i32_16x16x64_i8 v[80:83], v[188:191], v[212:215], v[80:83]
	v_mfma_i32_16x16x64_i8 v[68:71], v[180:183], v[220:223], v[68:71]
	v_mfma_i32_16x16x64_i8 v[64:67], v[188:191], v[220:223], v[64:67]
	s_barrier
	ds_read_b128 v[192:195], v165 offset:16384
	ds_read_b128 v[196:199], v165 offset:17408
	ds_read_b128 v[200:203], v165 offset:18432
	ds_read_b128 v[204:207], v165 offset:19456
	ds_read_b128 v[208:211], v165 offset:20480
	ds_read_b128 v[212:215], v165 offset:21504
	ds_read_b128 v[216:219], v165 offset:22528
	ds_read_b128 v[220:223], v165 offset:23552
	s_mov_b32 m0, s55
	s_nop 0
	global_load_lds_dwordx4 v[152:153], off
	s_add_i32 m0, s55, 0x2000
	s_add_i32 s55, s47, s35
	global_load_lds_dwordx4 v[224:225], off
	s_mov_b32 m0, s55
	s_nop 0
	global_load_lds_dwordx4 v[248:249], off
	s_add_i32 m0, s55, 0x2000
	s_nop 0
	global_load_lds_dwordx4 v[250:251], off
	s_mov_b32 m0, s38
	s_nop 0
	global_load_lds_dwordx4 v[226:227], off
	s_mov_b32 m0, s39
	s_nop 0
	global_load_lds_dwordx4 v[228:229], off
	s_waitcnt vmcnt(8)
	s_waitcnt lgkmcnt(0)
	s_barrier
	s_waitcnt lgkmcnt(0)
	v_mfma_i32_16x16x64_i8 v[60:63], v[144:147], v[192:195], v[60:63]
	v_mfma_i32_16x16x64_i8 v[56:59], v[168:171], v[192:195], v[56:59]
	v_mfma_i32_16x16x64_i8 v[44:47], v[144:147], v[200:203], v[44:47]
	v_mfma_i32_16x16x64_i8 v[40:43], v[168:171], v[200:203], v[40:43]
	s_add_i32 s55, 0, 0x18000
	v_mfma_i32_16x16x64_i8 v[28:31], v[144:147], v[208:211], v[28:31]
	v_mfma_i32_16x16x64_i8 v[24:27], v[168:171], v[208:211], v[24:27]
	v_add_u32_e32 v154, s55, v157
	v_mfma_i32_16x16x64_i8 v[12:15], v[144:147], v[216:219], v[12:15]
	v_mfma_i32_16x16x64_i8 v[8:11], v[168:171], v[216:219], v[8:11]
	s_add_i32 s56, 0, 0x1c000
	v_mfma_i32_16x16x64_i8 v[60:63], v[148:151], v[196:199], v[60:63]
	v_mfma_i32_16x16x64_i8 v[56:59], v[172:175], v[196:199], v[56:59]
	s_add_u32 s28, s28, 0x80000
	v_mfma_i32_16x16x64_i8 v[44:47], v[148:151], v[204:207], v[44:47]
	v_mfma_i32_16x16x64_i8 v[40:43], v[172:175], v[204:207], v[40:43]
	s_addc_u32 s29, s29, 0
	v_mfma_i32_16x16x64_i8 v[28:31], v[148:151], v[212:215], v[28:31]
	v_mfma_i32_16x16x64_i8 v[24:27], v[172:175], v[212:215], v[24:27]
	v_lshl_add_u64 v[248:249], s[28:29], 0, v[134:135]
	v_mfma_i32_16x16x64_i8 v[12:15], v[148:151], v[220:223], v[12:15]
	v_mfma_i32_16x16x64_i8 v[8:11], v[172:175], v[220:223], v[8:11]
	v_lshl_add_u64 v[230:231], s[28:29], 0, v[130:131]
	v_mfma_i32_16x16x64_i8 v[52:55], v[176:179], v[192:195], v[52:55]
	v_mfma_i32_16x16x64_i8 v[48:51], v[184:187], v[192:195], v[48:51]
	v_mfma_i32_16x16x64_i8 v[36:39], v[176:179], v[200:203], v[36:39]
	v_mfma_i32_16x16x64_i8 v[32:35], v[184:187], v[200:203], v[32:35]
	v_mfma_i32_16x16x64_i8 v[20:23], v[176:179], v[208:211], v[20:23]
	v_mfma_i32_16x16x64_i8 v[16:19], v[184:187], v[208:211], v[16:19]
	v_mfma_i32_16x16x64_i8 v[4:7], v[176:179], v[216:219], v[4:7]
	v_mfma_i32_16x16x64_i8 v[0:3], v[184:187], v[216:219], v[0:3]
	v_mfma_i32_16x16x64_i8 v[52:55], v[180:183], v[196:199], v[52:55]
	v_mfma_i32_16x16x64_i8 v[48:51], v[188:191], v[196:199], v[48:51]
	v_mfma_i32_16x16x64_i8 v[36:39], v[180:183], v[204:207], v[36:39]
	v_mfma_i32_16x16x64_i8 v[32:35], v[188:191], v[204:207], v[32:35]
	v_mfma_i32_16x16x64_i8 v[20:23], v[180:183], v[212:215], v[20:23]
	v_mfma_i32_16x16x64_i8 v[16:19], v[188:191], v[212:215], v[16:19]
	v_mfma_i32_16x16x64_i8 v[4:7], v[180:183], v[220:223], v[4:7]
	v_mfma_i32_16x16x64_i8 v[0:3], v[188:191], v[220:223], v[0:3]
	s_barrier
	ds_read_b128 v[192:195], v165 offset:32768
	ds_read_b128 v[196:199], v165 offset:33792
	ds_read_b128 v[200:203], v165 offset:34816
	ds_read_b128 v[204:207], v165 offset:35840
	ds_read_b128 v[208:211], v165 offset:36864
	ds_read_b128 v[212:215], v165 offset:37888
	ds_read_b128 v[216:219], v165 offset:38912
	ds_read_b128 v[220:223], v165 offset:39936
	ds_read_b128 v[144:147], v154
	ds_read_b128 v[148:151], v154 offset:1024
	ds_read_b128 v[168:171], v154 offset:2048
	ds_read_b128 v[172:175], v154 offset:3072
	v_add_u32_e32 v154, s56, v157
	ds_read_b128 v[176:179], v154
	ds_read_b128 v[180:183], v154 offset:1024
	ds_read_b128 v[184:187], v154 offset:2048
	ds_read_b128 v[188:191], v154 offset:3072
	s_mov_b32 m0, s40
	s_nop 0
	global_load_lds_dwordx4 v[248:249], off
	s_mov_b32 m0, s41
	s_nop 0
	global_load_lds_dwordx4 v[230:231], off
	s_waitcnt vmcnt(8)
	s_waitcnt lgkmcnt(0)
	s_barrier
	s_waitcnt lgkmcnt(0)
	v_mfma_i32_16x16x64_i8 v[124:127], v[144:147], v[192:195], v[124:127]
	v_mfma_i32_16x16x64_i8 v[120:123], v[168:171], v[192:195], v[120:123]
	v_mfma_i32_16x16x64_i8 v[108:111], v[144:147], v[200:203], v[108:111]
	v_mfma_i32_16x16x64_i8 v[104:107], v[168:171], v[200:203], v[104:107]
	s_add_i32 s28, s55, s35
	v_mfma_i32_16x16x64_i8 v[92:95], v[144:147], v[208:211], v[92:95]
	v_mfma_i32_16x16x64_i8 v[88:91], v[168:171], v[208:211], v[88:91]
	v_lshl_add_u64 v[248:249], v[152:153], 0, s[16:17]
	v_mfma_i32_16x16x64_i8 v[76:79], v[144:147], v[216:219], v[76:79]
	v_mfma_i32_16x16x64_i8 v[72:75], v[168:171], v[216:219], v[72:75]
	s_add_u32 s6, s6, 0x80080
	v_mfma_i32_16x16x64_i8 v[124:127], v[148:151], v[196:199], v[124:127]
	v_mfma_i32_16x16x64_i8 v[120:123], v[172:175], v[196:199], v[120:123]
	v_lshl_add_u64 v[250:251], v[224:225], 0, s[16:17]
	v_mfma_i32_16x16x64_i8 v[108:111], v[148:151], v[204:207], v[108:111]
	v_mfma_i32_16x16x64_i8 v[104:107], v[172:175], v[204:207], v[104:107]
	s_addc_u32 s7, s7, 0
	v_mfma_i32_16x16x64_i8 v[92:95], v[148:151], v[212:215], v[92:95]
	v_mfma_i32_16x16x64_i8 v[88:91], v[172:175], v[212:215], v[88:91]
	v_lshl_add_u64 v[252:253], s[6:7], 0, v[132:133]
	v_mfma_i32_16x16x64_i8 v[76:79], v[148:151], v[220:223], v[76:79]
	v_mfma_i32_16x16x64_i8 v[72:75], v[172:175], v[220:223], v[72:75]
	v_lshl_add_u64 v[152:153], s[6:7], 0, v[128:129]
	v_mfma_i32_16x16x64_i8 v[116:119], v[176:179], v[192:195], v[116:119]
	v_mfma_i32_16x16x64_i8 v[112:115], v[184:187], v[192:195], v[112:115]
	v_mfma_i32_16x16x64_i8 v[100:103], v[176:179], v[200:203], v[100:103]
	v_mfma_i32_16x16x64_i8 v[96:99], v[184:187], v[200:203], v[96:99]
	v_mfma_i32_16x16x64_i8 v[84:87], v[176:179], v[208:211], v[84:87]
	v_mfma_i32_16x16x64_i8 v[80:83], v[184:187], v[208:211], v[80:83]
	v_mfma_i32_16x16x64_i8 v[68:71], v[176:179], v[216:219], v[68:71]
	v_mfma_i32_16x16x64_i8 v[64:67], v[184:187], v[216:219], v[64:67]
	v_mfma_i32_16x16x64_i8 v[116:119], v[180:183], v[196:199], v[116:119]
	v_mfma_i32_16x16x64_i8 v[112:115], v[188:191], v[196:199], v[112:115]
	v_mfma_i32_16x16x64_i8 v[100:103], v[180:183], v[204:207], v[100:103]
	v_mfma_i32_16x16x64_i8 v[96:99], v[188:191], v[204:207], v[96:99]
	v_mfma_i32_16x16x64_i8 v[84:87], v[180:183], v[212:215], v[84:87]
	v_mfma_i32_16x16x64_i8 v[80:83], v[188:191], v[212:215], v[80:83]
	v_mfma_i32_16x16x64_i8 v[68:71], v[180:183], v[220:223], v[68:71]
	v_mfma_i32_16x16x64_i8 v[64:67], v[188:191], v[220:223], v[64:67]
	s_barrier
	ds_read_b128 v[192:195], v165 offset:49152
	ds_read_b128 v[196:199], v165 offset:50176
	ds_read_b128 v[200:203], v165 offset:51200
	ds_read_b128 v[204:207], v165 offset:52224
	ds_read_b128 v[208:211], v165 offset:53248
	ds_read_b128 v[212:215], v165 offset:54272
	ds_read_b128 v[216:219], v165 offset:55296
	ds_read_b128 v[220:223], v165 offset:56320
	s_mov_b32 m0, s28
	s_nop 0
	global_load_lds_dwordx4 v[248:249], off
	s_add_i32 m0, s28, 0x2000
	s_add_i32 s28, s56, s35
	global_load_lds_dwordx4 v[250:251], off
	s_mov_b32 m0, s28
	s_nop 0
	global_load_lds_dwordx4 v[252:253], off
	s_add_i32 m0, s28, 0x2000
	s_nop 0
	global_load_lds_dwordx4 v[152:153], off
	v_lshl_add_u64 v[152:153], v[226:227], 0, s[16:17]
	s_mov_b32 m0, s43
	s_nop 0
	global_load_lds_dwordx4 v[152:153], off
	v_lshl_add_u64 v[152:153], v[228:229], 0, s[16:17]
	s_mov_b32 m0, s44
	s_nop 0
	global_load_lds_dwordx4 v[152:153], off
	s_waitcnt vmcnt(8)
	s_waitcnt lgkmcnt(0)
	s_barrier
	s_waitcnt lgkmcnt(0)
	v_mfma_i32_16x16x64_i8 v[60:63], v[144:147], v[192:195], v[60:63]
	v_mfma_i32_16x16x64_i8 v[56:59], v[168:171], v[192:195], v[56:59]
	v_mfma_i32_16x16x64_i8 v[44:47], v[144:147], v[200:203], v[44:47]
	v_mfma_i32_16x16x64_i8 v[40:43], v[168:171], v[200:203], v[40:43]
	v_mfma_i32_16x16x64_i8 v[28:31], v[144:147], v[208:211], v[28:31]
	v_mfma_i32_16x16x64_i8 v[24:27], v[168:171], v[208:211], v[24:27]
	v_mfma_i32_16x16x64_i8 v[12:15], v[144:147], v[216:219], v[12:15]
	v_mfma_i32_16x16x64_i8 v[8:11], v[168:171], v[216:219], v[8:11]
	v_mfma_i32_16x16x64_i8 v[60:63], v[148:151], v[196:199], v[60:63]
	v_mfma_i32_16x16x64_i8 v[56:59], v[172:175], v[196:199], v[56:59]
	v_mfma_i32_16x16x64_i8 v[44:47], v[148:151], v[204:207], v[44:47]
	v_mfma_i32_16x16x64_i8 v[40:43], v[172:175], v[204:207], v[40:43]
	v_mfma_i32_16x16x64_i8 v[28:31], v[148:151], v[212:215], v[28:31]
	v_mfma_i32_16x16x64_i8 v[24:27], v[172:175], v[212:215], v[24:27]
	v_mfma_i32_16x16x64_i8 v[12:15], v[148:151], v[220:223], v[12:15]
	v_mfma_i32_16x16x64_i8 v[8:11], v[172:175], v[220:223], v[8:11]
	v_mfma_i32_16x16x64_i8 v[52:55], v[176:179], v[192:195], v[52:55]
	v_mfma_i32_16x16x64_i8 v[48:51], v[184:187], v[192:195], v[48:51]
	v_mfma_i32_16x16x64_i8 v[36:39], v[176:179], v[200:203], v[36:39]
	v_mfma_i32_16x16x64_i8 v[32:35], v[184:187], v[200:203], v[32:35]
	v_mfma_i32_16x16x64_i8 v[20:23], v[176:179], v[208:211], v[20:23]
	v_mfma_i32_16x16x64_i8 v[16:19], v[184:187], v[208:211], v[16:19]
	v_mfma_i32_16x16x64_i8 v[4:7], v[176:179], v[216:219], v[4:7]
	v_mfma_i32_16x16x64_i8 v[0:3], v[184:187], v[216:219], v[0:3]
	v_mfma_i32_16x16x64_i8 v[52:55], v[180:183], v[196:199], v[52:55]
	v_mfma_i32_16x16x64_i8 v[48:51], v[188:191], v[196:199], v[48:51]
	v_mfma_i32_16x16x64_i8 v[36:39], v[180:183], v[204:207], v[36:39]
	v_mfma_i32_16x16x64_i8 v[32:35], v[188:191], v[204:207], v[32:35]
	v_mfma_i32_16x16x64_i8 v[20:23], v[180:183], v[212:215], v[20:23]
	v_mfma_i32_16x16x64_i8 v[16:19], v[188:191], v[212:215], v[16:19]
	v_mfma_i32_16x16x64_i8 v[4:7], v[180:183], v[220:223], v[4:7]
	v_mfma_i32_16x16x64_i8 v[0:3], v[188:191], v[220:223], v[0:3]
	s_barrier
	s_add_i32 s54, s54, 2
	s_add_u32 s52, s52, 0x100
	s_addc_u32 s53, s53, 0
	s_add_u32 s4, s4, 0x100
	s_addc_u32 s5, s5, 0
	s_cmp_gt_u32 s54, 29
	s_cbranch_scc0 .LBB0_726
	s_setprio 0
	s_and_b64 vcc, exec, s[18:19]
	s_cbranch_vccz .LBB0_729
	s_barrier

.Lsp_skip8:
.LBB0_1356:
	ds_read_b128 v[144:147], v180
	ds_read_b128 v[148:151], v180 offset:1024
	ds_read_b128 v[152:155], v180 offset:2048
	ds_read_b128 v[156:159], v180 offset:3072
	ds_read_b128 v[160:163], v181
	ds_read_b128 v[164:167], v181 offset:1024
	ds_read_b128 v[168:171], v181 offset:2048
	ds_read_b128 v[172:175], v181 offset:3072
	ds_read_b128 v[186:189], v182
	ds_read_b128 v[190:193], v182 offset:1024
	ds_read_b128 v[194:197], v182 offset:2048
	ds_read_b128 v[198:201], v182 offset:3072
	ds_read_b128 v[202:205], v182 offset:4096
	ds_read_b128 v[206:209], v182 offset:5120
	ds_read_b128 v[210:213], v182 offset:6144
	ds_read_b128 v[214:217], v182 offset:7168
	s_add_u32 s34, s30, 0xfff80080
	s_addc_u32 s35, s31, -1
	s_cmp_eq_u32 s58, 28
	s_cselect_b32 s37, s1, s35
	s_cselect_b32 s36, s23, s34
	s_cselect_b32 s35, s21, s57
	s_cselect_b32 s34, s29, s33
	v_lshl_add_u64 v[218:219], s[30:31], 0, v[138:139]
	s_add_i32 m0, s43, 0xc000
	s_nop 0
	global_load_lds_dwordx4 v[218:219], off
	v_lshl_add_u64 v[218:219], s[30:31], 0, v[136:137]
	s_add_i32 m0, s43, 0xe000
	s_nop 0
	global_load_lds_dwordx4 v[218:219], off
	s_waitcnt vmcnt(8)
	s_waitcnt lgkmcnt(0)
	s_barrier
	s_waitcnt lgkmcnt(0)
	v_mfma_i32_16x16x64_i8 v[124:127], v[144:147], v[186:189], v[124:127]
	v_mfma_i32_16x16x64_i8 v[120:123], v[152:155], v[186:189], v[120:123]
	v_mfma_i32_16x16x64_i8 v[108:111], v[144:147], v[194:197], v[108:111]
	v_mfma_i32_16x16x64_i8 v[104:107], v[152:155], v[194:197], v[104:107]
	s_add_i32 s59, s52, s42
	v_mfma_i32_16x16x64_i8 v[92:95], v[144:147], v[202:205], v[92:95]
	v_mfma_i32_16x16x64_i8 v[88:91], v[152:155], v[202:205], v[88:91]
	v_lshl_add_u64 v[218:219], s[34:35], 0, v[130:131]
	v_mfma_i32_16x16x64_i8 v[76:79], v[144:147], v[210:213], v[76:79]
	v_mfma_i32_16x16x64_i8 v[72:75], v[152:155], v[210:213], v[72:75]
	s_add_u32 s60, s34, 0x80000
	v_mfma_i32_16x16x64_i8 v[124:127], v[148:151], v[190:193], v[124:127]
	v_mfma_i32_16x16x64_i8 v[120:123], v[156:159], v[190:193], v[120:123]
	v_lshl_add_u64 v[220:221], s[34:35], 0, v[134:135]
	v_mfma_i32_16x16x64_i8 v[108:111], v[148:151], v[198:201], v[108:111]
	v_mfma_i32_16x16x64_i8 v[104:107], v[156:159], v[198:201], v[104:107]
	s_addc_u32 s61, s35, 0
	v_mfma_i32_16x16x64_i8 v[92:95], v[148:151], v[206:209], v[92:95]
	v_mfma_i32_16x16x64_i8 v[88:91], v[156:159], v[206:209], v[88:91]
	v_lshl_add_u64 v[248:249], s[60:61], 0, v[130:131]
	v_mfma_i32_16x16x64_i8 v[76:79], v[148:151], v[214:217], v[76:79]
	v_mfma_i32_16x16x64_i8 v[72:75], v[156:159], v[214:217], v[72:75]
	v_lshl_add_u64 v[224:225], s[36:37], 0, v[132:133]
	v_mfma_i32_16x16x64_i8 v[116:119], v[160:163], v[186:189], v[116:119]
	v_mfma_i32_16x16x64_i8 v[112:115], v[168:171], v[186:189], v[112:115]
	v_lshl_add_u64 v[250:251], s[60:61], 0, v[134:135]
	v_mfma_i32_16x16x64_i8 v[100:103], v[160:163], v[194:197], v[100:103]
	v_mfma_i32_16x16x64_i8 v[96:99], v[168:171], v[194:197], v[96:99]
	v_lshl_add_u64 v[222:223], s[36:37], 0, v[128:129]
	v_mfma_i32_16x16x64_i8 v[84:87], v[160:163], v[202:205], v[84:87]
	v_mfma_i32_16x16x64_i8 v[80:83], v[168:171], v[202:205], v[80:83]
	v_mfma_i32_16x16x64_i8 v[68:71], v[160:163], v[210:213], v[68:71]
	v_mfma_i32_16x16x64_i8 v[64:67], v[168:171], v[210:213], v[64:67]
	v_mfma_i32_16x16x64_i8 v[116:119], v[164:167], v[190:193], v[116:119]
	v_mfma_i32_16x16x64_i8 v[112:115], v[172:175], v[190:193], v[112:115]
	v_mfma_i32_16x16x64_i8 v[100:103], v[164:167], v[198:201], v[100:103]
	v_mfma_i32_16x16x64_i8 v[96:99], v[172:175], v[198:201], v[96:99]
	v_mfma_i32_16x16x64_i8 v[84:87], v[164:167], v[206:209], v[84:87]
	v_mfma_i32_16x16x64_i8 v[80:83], v[172:175], v[206:209], v[80:83]
	v_mfma_i32_16x16x64_i8 v[68:71], v[164:167], v[214:217], v[68:71]
	v_mfma_i32_16x16x64_i8 v[64:67], v[172:175], v[214:217], v[64:67]
	s_barrier
	ds_read_b128 v[186:189], v182 offset:16384
	ds_read_b128 v[190:193], v182 offset:17408
	ds_read_b128 v[194:197], v182 offset:18432
	ds_read_b128 v[198:201], v182 offset:19456
	ds_read_b128 v[202:205], v182 offset:20480
	ds_read_b128 v[206:209], v182 offset:21504
	ds_read_b128 v[210:213], v182 offset:22528
	ds_read_b128 v[214:217], v182 offset:23552
	s_mov_b32 m0, s59
	s_nop 0
	global_load_lds_dwordx4 v[218:219], off
	s_add_i32 m0, s59, 0x2000
	s_add_i32 s59, s53, s42
	global_load_lds_dwordx4 v[220:221], off
	s_mov_b32 m0, s59
	s_nop 0
	global_load_lds_dwordx4 v[248:249], off
	s_add_i32 m0, s59, 0x2000
	s_nop 0
	global_load_lds_dwordx4 v[250:251], off
	s_mov_b32 m0, s43
	s_nop 0
	global_load_lds_dwordx4 v[222:223], off
	s_mov_b32 m0, s44
	s_nop 0
	global_load_lds_dwordx4 v[224:225], off
	s_waitcnt vmcnt(8)
	s_waitcnt lgkmcnt(0)
	s_barrier
	s_waitcnt lgkmcnt(0)
	v_mfma_i32_16x16x64_i8 v[60:63], v[144:147], v[186:189], v[60:63]
	v_mfma_i32_16x16x64_i8 v[56:59], v[152:155], v[186:189], v[56:59]
	v_mfma_i32_16x16x64_i8 v[44:47], v[144:147], v[194:197], v[44:47]
	v_mfma_i32_16x16x64_i8 v[40:43], v[152:155], v[194:197], v[40:43]
	s_add_i32 s59, 0, 0x18000
	v_mfma_i32_16x16x64_i8 v[28:31], v[144:147], v[202:205], v[28:31]
	v_mfma_i32_16x16x64_i8 v[24:27], v[152:155], v[202:205], v[24:27]
	s_add_i32 s60, 0, 0x1c000
	v_mfma_i32_16x16x64_i8 v[12:15], v[144:147], v[210:213], v[12:15]
	v_mfma_i32_16x16x64_i8 v[8:11], v[152:155], v[210:213], v[8:11]
	s_add_u32 s36, s36, 0x80000
	v_mfma_i32_16x16x64_i8 v[60:63], v[148:151], v[190:193], v[60:63]
	v_mfma_i32_16x16x64_i8 v[56:59], v[156:159], v[190:193], v[56:59]
	s_addc_u32 s37, s37, 0
	v_mfma_i32_16x16x64_i8 v[44:47], v[148:151], v[198:201], v[44:47]
	v_mfma_i32_16x16x64_i8 v[40:43], v[156:159], v[198:201], v[40:43]
	v_lshl_add_u64 v[248:249], s[36:37], 0, v[128:129]
	v_mfma_i32_16x16x64_i8 v[28:31], v[148:151], v[206:209], v[28:31]
	v_mfma_i32_16x16x64_i8 v[24:27], v[156:159], v[206:209], v[24:27]
	v_lshl_add_u64 v[226:227], s[36:37], 0, v[132:133]
	v_mfma_i32_16x16x64_i8 v[12:15], v[148:151], v[214:217], v[12:15]
	v_mfma_i32_16x16x64_i8 v[8:11], v[156:159], v[214:217], v[8:11]
	v_mfma_i32_16x16x64_i8 v[52:55], v[160:163], v[186:189], v[52:55]
	v_mfma_i32_16x16x64_i8 v[48:51], v[168:171], v[186:189], v[48:51]
	v_mfma_i32_16x16x64_i8 v[36:39], v[160:163], v[194:197], v[36:39]
	v_mfma_i32_16x16x64_i8 v[32:35], v[168:171], v[194:197], v[32:35]
	v_mfma_i32_16x16x64_i8 v[20:23], v[160:163], v[202:205], v[20:23]
	v_mfma_i32_16x16x64_i8 v[16:19], v[168:171], v[202:205], v[16:19]
	v_mfma_i32_16x16x64_i8 v[4:7], v[160:163], v[210:213], v[4:7]
	v_mfma_i32_16x16x64_i8 v[0:3], v[168:171], v[210:213], v[0:3]
	v_mfma_i32_16x16x64_i8 v[52:55], v[164:167], v[190:193], v[52:55]
	v_mfma_i32_16x16x64_i8 v[48:51], v[172:175], v[190:193], v[48:51]
	v_mfma_i32_16x16x64_i8 v[36:39], v[164:167], v[198:201], v[36:39]
	v_mfma_i32_16x16x64_i8 v[32:35], v[172:175], v[198:201], v[32:35]
	v_mfma_i32_16x16x64_i8 v[20:23], v[164:167], v[206:209], v[20:23]
	v_mfma_i32_16x16x64_i8 v[16:19], v[172:175], v[206:209], v[16:19]
	v_mfma_i32_16x16x64_i8 v[4:7], v[164:167], v[214:217], v[4:7]
	v_mfma_i32_16x16x64_i8 v[0:3], v[172:175], v[214:217], v[0:3]
	s_barrier
	ds_read_b128 v[186:189], v182 offset:32768
	ds_read_b128 v[190:193], v182 offset:33792
	ds_read_b128 v[194:197], v182 offset:34816
	ds_read_b128 v[198:201], v182 offset:35840
	ds_read_b128 v[202:205], v182 offset:36864
	ds_read_b128 v[206:209], v182 offset:37888
	ds_read_b128 v[210:213], v182 offset:38912
	ds_read_b128 v[214:217], v182 offset:39936
	v_add_u32_e32 v156, s59, v178
	v_add_u32_e32 v172, s60, v178
	ds_read_b128 v[144:147], v156
	ds_read_b128 v[148:151], v156 offset:1024
	ds_read_b128 v[152:155], v156 offset:2048
	ds_read_b128 v[156:159], v156 offset:3072
	ds_read_b128 v[160:163], v172
	ds_read_b128 v[164:167], v172 offset:1024
	ds_read_b128 v[168:171], v172 offset:2048
	ds_read_b128 v[172:175], v172 offset:3072
	s_mov_b32 m0, s45
	s_nop 0
	global_load_lds_dwordx4 v[248:249], off
	s_mov_b32 m0, s46
	s_nop 0
	global_load_lds_dwordx4 v[226:227], off
	s_waitcnt vmcnt(8)
	s_waitcnt lgkmcnt(0)
	s_barrier
	s_waitcnt lgkmcnt(0)
	v_mfma_i32_16x16x64_i8 v[124:127], v[144:147], v[186:189], v[124:127]
	v_mfma_i32_16x16x64_i8 v[120:123], v[152:155], v[186:189], v[120:123]
	v_mfma_i32_16x16x64_i8 v[108:111], v[144:147], v[194:197], v[108:111]
	v_mfma_i32_16x16x64_i8 v[104:107], v[152:155], v[194:197], v[104:107]
	s_add_i32 s36, s59, s42
	v_mfma_i32_16x16x64_i8 v[92:95], v[144:147], v[202:205], v[92:95]
	v_mfma_i32_16x16x64_i8 v[88:91], v[152:155], v[202:205], v[88:91]
	v_lshl_add_u64 v[248:249], v[218:219], 0, s[16:17]
	v_mfma_i32_16x16x64_i8 v[76:79], v[144:147], v[210:213], v[76:79]
	v_mfma_i32_16x16x64_i8 v[72:75], v[152:155], v[210:213], v[72:75]
	s_add_u32 s34, s34, 0x80080
	v_mfma_i32_16x16x64_i8 v[124:127], v[148:151], v[190:193], v[124:127]
	v_mfma_i32_16x16x64_i8 v[120:123], v[156:159], v[190:193], v[120:123]
	v_lshl_add_u64 v[250:251], v[220:221], 0, s[16:17]
	v_mfma_i32_16x16x64_i8 v[108:111], v[148:151], v[198:201], v[108:111]
	v_mfma_i32_16x16x64_i8 v[104:107], v[156:159], v[198:201], v[104:107]
	s_addc_u32 s35, s35, 0
	v_mfma_i32_16x16x64_i8 v[92:95], v[148:151], v[206:209], v[92:95]
	v_mfma_i32_16x16x64_i8 v[88:91], v[156:159], v[206:209], v[88:91]
	v_lshl_add_u64 v[252:253], s[34:35], 0, v[130:131]
	v_mfma_i32_16x16x64_i8 v[76:79], v[148:151], v[214:217], v[76:79]
	v_mfma_i32_16x16x64_i8 v[72:75], v[156:159], v[214:217], v[72:75]
	v_lshl_add_u64 v[228:229], s[34:35], 0, v[134:135]
	v_mfma_i32_16x16x64_i8 v[116:119], v[160:163], v[186:189], v[116:119]
	v_mfma_i32_16x16x64_i8 v[112:115], v[168:171], v[186:189], v[112:115]
	v_lshl_add_u64 v[230:231], v[222:223], 0, s[16:17]
	v_mfma_i32_16x16x64_i8 v[100:103], v[160:163], v[194:197], v[100:103]
	v_mfma_i32_16x16x64_i8 v[96:99], v[168:171], v[194:197], v[96:99]
	v_lshl_add_u64 v[218:219], v[224:225], 0, s[16:17]
	v_mfma_i32_16x16x64_i8 v[84:87], v[160:163], v[202:205], v[84:87]
	v_mfma_i32_16x16x64_i8 v[80:83], v[168:171], v[202:205], v[80:83]
	v_mfma_i32_16x16x64_i8 v[68:71], v[160:163], v[210:213], v[68:71]
	v_mfma_i32_16x16x64_i8 v[64:67], v[168:171], v[210:213], v[64:67]
	v_mfma_i32_16x16x64_i8 v[116:119], v[164:167], v[190:193], v[116:119]
	v_mfma_i32_16x16x64_i8 v[112:115], v[172:175], v[190:193], v[112:115]
	v_mfma_i32_16x16x64_i8 v[100:103], v[164:167], v[198:201], v[100:103]
	v_mfma_i32_16x16x64_i8 v[96:99], v[172:175], v[198:201], v[96:99]
	v_mfma_i32_16x16x64_i8 v[84:87], v[164:167], v[206:209], v[84:87]
	v_mfma_i32_16x16x64_i8 v[80:83], v[172:175], v[206:209], v[80:83]
	v_mfma_i32_16x16x64_i8 v[68:71], v[164:167], v[214:217], v[68:71]
	v_mfma_i32_16x16x64_i8 v[64:67], v[172:175], v[214:217], v[64:67]
	s_barrier
	ds_read_b128 v[186:189], v182 offset:49152
	ds_read_b128 v[190:193], v182 offset:50176
	ds_read_b128 v[194:197], v182 offset:51200
	ds_read_b128 v[198:201], v182 offset:52224
	ds_read_b128 v[202:205], v182 offset:53248
	ds_read_b128 v[206:209], v182 offset:54272
	ds_read_b128 v[210:213], v182 offset:55296
	ds_read_b128 v[214:217], v182 offset:56320
	s_mov_b32 m0, s36
	s_nop 0
	global_load_lds_dwordx4 v[248:249], off
	s_add_i32 m0, s36, 0x2000
	s_add_i32 s36, s60, s42
	global_load_lds_dwordx4 v[250:251], off
	s_mov_b32 m0, s36
	s_nop 0
	global_load_lds_dwordx4 v[252:253], off
	s_add_i32 m0, s36, 0x2000
	s_nop 0
	global_load_lds_dwordx4 v[228:229], off
	s_mov_b32 m0, s48
	s_nop 0
	global_load_lds_dwordx4 v[230:231], off
	s_mov_b32 m0, s49
	s_nop 0
	global_load_lds_dwordx4 v[218:219], off
	s_waitcnt vmcnt(8)
	s_waitcnt lgkmcnt(0)
	s_barrier
	s_waitcnt lgkmcnt(0)
	v_mfma_i32_16x16x64_i8 v[60:63], v[144:147], v[186:189], v[60:63]
	v_mfma_i32_16x16x64_i8 v[56:59], v[152:155], v[186:189], v[56:59]
	v_mfma_i32_16x16x64_i8 v[44:47], v[144:147], v[194:197], v[44:47]
	v_mfma_i32_16x16x64_i8 v[40:43], v[152:155], v[194:197], v[40:43]
	v_mfma_i32_16x16x64_i8 v[28:31], v[144:147], v[202:205], v[28:31]
	v_mfma_i32_16x16x64_i8 v[24:27], v[152:155], v[202:205], v[24:27]
	v_mfma_i32_16x16x64_i8 v[12:15], v[144:147], v[210:213], v[12:15]
	v_mfma_i32_16x16x64_i8 v[8:11], v[152:155], v[210:213], v[8:11]
	v_mfma_i32_16x16x64_i8 v[60:63], v[148:151], v[190:193], v[60:63]
	v_mfma_i32_16x16x64_i8 v[56:59], v[156:159], v[190:193], v[56:59]
	v_mfma_i32_16x16x64_i8 v[44:47], v[148:151], v[198:201], v[44:47]
	v_mfma_i32_16x16x64_i8 v[40:43], v[156:159], v[198:201], v[40:43]
	v_mfma_i32_16x16x64_i8 v[28:31], v[148:151], v[206:209], v[28:31]
	v_mfma_i32_16x16x64_i8 v[24:27], v[156:159], v[206:209], v[24:27]
	v_mfma_i32_16x16x64_i8 v[12:15], v[148:151], v[214:217], v[12:15]
	v_mfma_i32_16x16x64_i8 v[8:11], v[156:159], v[214:217], v[8:11]
	v_mfma_i32_16x16x64_i8 v[52:55], v[160:163], v[186:189], v[52:55]
	v_mfma_i32_16x16x64_i8 v[48:51], v[168:171], v[186:189], v[48:51]
	v_mfma_i32_16x16x64_i8 v[36:39], v[160:163], v[194:197], v[36:39]
	v_mfma_i32_16x16x64_i8 v[32:35], v[168:171], v[194:197], v[32:35]
	v_mfma_i32_16x16x64_i8 v[20:23], v[160:163], v[202:205], v[20:23]
	v_mfma_i32_16x16x64_i8 v[16:19], v[168:171], v[202:205], v[16:19]
	v_mfma_i32_16x16x64_i8 v[4:7], v[160:163], v[210:213], v[4:7]
	v_mfma_i32_16x16x64_i8 v[0:3], v[168:171], v[210:213], v[0:3]
	v_mfma_i32_16x16x64_i8 v[52:55], v[164:167], v[190:193], v[52:55]
	v_mfma_i32_16x16x64_i8 v[48:51], v[172:175], v[190:193], v[48:51]
	v_mfma_i32_16x16x64_i8 v[36:39], v[164:167], v[198:201], v[36:39]
	v_mfma_i32_16x16x64_i8 v[32:35], v[172:175], v[198:201], v[32:35]
	v_mfma_i32_16x16x64_i8 v[20:23], v[164:167], v[206:209], v[20:23]
	v_mfma_i32_16x16x64_i8 v[16:19], v[172:175], v[206:209], v[16:19]
	v_mfma_i32_16x16x64_i8 v[4:7], v[164:167], v[214:217], v[4:7]
	v_mfma_i32_16x16x64_i8 v[0:3], v[172:175], v[214:217], v[0:3]
	s_barrier
	s_add_i32 s58, s58, 2
	s_add_u32 s33, s33, 0x100
	s_addc_u32 s57, s57, 0
	s_add_u32 s30, s30, 0x100
	s_addc_u32 s31, s31, 0
	s_cmp_gt_u32 s58, 29
	s_cbranch_scc0 .LBB0_1356
	s_setprio 0
	s_and_b64 vcc, exec, s[18:19]
	s_cbranch_vccz .LBB0_1359
	s_barrier

.Lsp_skip9:
.LBB0_1841:
	ds_read_b128 v[186:189], v183
	ds_read_b128 v[190:193], v183 offset:1024
	ds_read_b128 v[194:197], v183 offset:2048
	ds_read_b128 v[198:201], v183 offset:3072
	ds_read_b128 v[202:205], v183 offset:4096
	ds_read_b128 v[206:209], v183 offset:5120
	ds_read_b128 v[210:213], v183 offset:6144
	ds_read_b128 v[214:217], v183 offset:7168
	v_add_u32_e32 v140, s47, v181
	v_add_u32_e32 v174, s48, v181
	ds_read_b128 v[124:127], v140
	ds_read_b128 v[132:135], v140 offset:1024
	ds_read_b128 v[136:139], v140 offset:2048
	ds_read_b128 v[140:143], v140 offset:3072
	ds_read_b128 v[162:165], v174
	ds_read_b128 v[166:169], v174 offset:1024
	ds_read_b128 v[170:173], v174 offset:2048
	ds_read_b128 v[174:177], v174 offset:3072
	s_add_u32 s30, s28, 0xffe00080
	s_addc_u32 s31, s29, -1
	s_cmpk_eq_i32 s53, 0x7c
	s_cselect_b32 s35, s19, s31
	s_cselect_b32 s34, s25, s30
	s_cselect_b32 s31, s17, s52
	s_cselect_b32 s30, s50, s51
	v_lshl_add_u64 v[178:179], s[28:29], 0, v[156:157]
	s_add_i32 m0, s27, 0xc000
	s_nop 0
	global_load_lds_dwordx4 v[178:179], off
	v_lshl_add_u64 v[178:179], s[28:29], 0, v[154:155]
	s_add_i32 m0, s27, 0xe000
	s_nop 0
	global_load_lds_dwordx4 v[178:179], off
	s_waitcnt vmcnt(8)
	s_waitcnt lgkmcnt(0)
	s_barrier
	s_waitcnt lgkmcnt(0)
	v_mfma_i32_16x16x64_i8 v[116:119], v[124:127], v[186:189], v[116:119]
	v_mfma_i32_16x16x64_i8 v[104:107], v[136:139], v[186:189], v[104:107]
	v_mfma_i32_16x16x64_i8 v[112:115], v[124:127], v[194:197], v[112:115]
	v_mfma_i32_16x16x64_i8 v[108:111], v[136:139], v[194:197], v[108:111]
	s_add_i32 s54, s47, s38
	v_mfma_i32_16x16x64_i8 v[92:95], v[124:127], v[202:205], v[92:95]
	v_mfma_i32_16x16x64_i8 v[88:91], v[136:139], v[202:205], v[88:91]
	v_lshl_add_u64 v[178:179], s[30:31], 0, v[146:147]
	v_mfma_i32_16x16x64_i8 v[76:79], v[124:127], v[210:213], v[76:79]
	v_mfma_i32_16x16x64_i8 v[72:75], v[136:139], v[210:213], v[72:75]
	v_lshl_add_u64 v[218:219], s[30:31], 0, v[150:151]
	v_mfma_i32_16x16x64_i8 v[116:119], v[132:135], v[190:193], v[116:119]
	v_mfma_i32_16x16x64_i8 v[104:107], v[140:143], v[190:193], v[104:107]
	s_add_i32 s56, s48, s38
	v_mfma_i32_16x16x64_i8 v[112:115], v[132:135], v[198:201], v[112:115]
	v_mfma_i32_16x16x64_i8 v[108:111], v[140:143], v[198:201], v[108:111]
	v_lshl_add_u64 v[222:223], s[34:35], 0, v[148:149]
	v_mfma_i32_16x16x64_i8 v[92:95], v[132:135], v[206:209], v[92:95]
	v_mfma_i32_16x16x64_i8 v[88:91], v[140:143], v[206:209], v[88:91]
	v_lshl_add_u64 v[220:221], s[34:35], 0, v[144:145]
	v_mfma_i32_16x16x64_i8 v[76:79], v[132:135], v[214:217], v[76:79]
	v_mfma_i32_16x16x64_i8 v[72:75], v[140:143], v[214:217], v[72:75]
	v_mfma_i32_16x16x64_i8 v[128:131], v[162:165], v[186:189], v[128:131]
	v_mfma_i32_16x16x64_i8 v[120:123], v[170:173], v[186:189], v[120:123]
	v_mfma_i32_16x16x64_i8 v[100:103], v[162:165], v[194:197], v[100:103]
	v_mfma_i32_16x16x64_i8 v[96:99], v[170:173], v[194:197], v[96:99]
	v_mfma_i32_16x16x64_i8 v[84:87], v[162:165], v[202:205], v[84:87]
	v_mfma_i32_16x16x64_i8 v[80:83], v[170:173], v[202:205], v[80:83]
	v_mfma_i32_16x16x64_i8 v[68:71], v[162:165], v[210:213], v[68:71]
	v_mfma_i32_16x16x64_i8 v[64:67], v[170:173], v[210:213], v[64:67]
	v_mfma_i32_16x16x64_i8 v[128:131], v[166:169], v[190:193], v[128:131]
	v_mfma_i32_16x16x64_i8 v[120:123], v[174:177], v[190:193], v[120:123]
	v_mfma_i32_16x16x64_i8 v[100:103], v[166:169], v[198:201], v[100:103]
	v_mfma_i32_16x16x64_i8 v[96:99], v[174:177], v[198:201], v[96:99]
	v_mfma_i32_16x16x64_i8 v[84:87], v[166:169], v[206:209], v[84:87]
	v_mfma_i32_16x16x64_i8 v[80:83], v[174:177], v[206:209], v[80:83]
	v_mfma_i32_16x16x64_i8 v[68:71], v[166:169], v[214:217], v[68:71]
	v_mfma_i32_16x16x64_i8 v[64:67], v[174:177], v[214:217], v[64:67]
	s_barrier
	ds_read_b128 v[186:189], v183 offset:16384
	ds_read_b128 v[190:193], v183 offset:17408
	ds_read_b128 v[194:197], v183 offset:18432
	ds_read_b128 v[198:201], v183 offset:19456
	ds_read_b128 v[202:205], v183 offset:20480
	ds_read_b128 v[206:209], v183 offset:21504
	ds_read_b128 v[210:213], v183 offset:22528
	ds_read_b128 v[214:217], v183 offset:23552
	s_mov_b32 m0, s54
	s_nop 0
	global_load_lds_dwordx4 v[178:179], off
	s_add_i32 m0, s54, 0x2000
	s_add_u32 s54, s30, 0x200000
	s_addc_u32 s55, s31, 0
	global_load_lds_dwordx4 v[218:219], off
	v_lshl_add_u64 v[248:249], s[54:55], 0, v[146:147]
	s_mov_b32 m0, s56
	s_nop 0
	global_load_lds_dwordx4 v[248:249], off
	v_lshl_add_u64 v[250:251], s[54:55], 0, v[150:151]
	s_add_i32 m0, s56, 0x2000
	s_nop 0
	global_load_lds_dwordx4 v[250:251], off
	s_mov_b32 m0, s27
	s_nop 0
	global_load_lds_dwordx4 v[220:221], off
	s_mov_b32 m0, s39
	s_nop 0
	global_load_lds_dwordx4 v[222:223], off
	s_waitcnt vmcnt(8)
	s_waitcnt lgkmcnt(0)
	s_barrier
	s_waitcnt lgkmcnt(0)
	v_mfma_i32_16x16x64_i8 v[60:63], v[124:127], v[186:189], v[60:63]
	v_mfma_i32_16x16x64_i8 v[56:59], v[136:139], v[186:189], v[56:59]
	v_mfma_i32_16x16x64_i8 v[44:47], v[124:127], v[194:197], v[44:47]
	v_mfma_i32_16x16x64_i8 v[40:43], v[136:139], v[194:197], v[40:43]
	s_add_i32 s54, 0, 0x18000
	v_mfma_i32_16x16x64_i8 v[28:31], v[124:127], v[202:205], v[28:31]
	v_mfma_i32_16x16x64_i8 v[24:27], v[136:139], v[202:205], v[24:27]
	s_add_i32 s55, 0, 0x1c000
	v_mfma_i32_16x16x64_i8 v[12:15], v[124:127], v[210:213], v[12:15]
	v_mfma_i32_16x16x64_i8 v[8:11], v[136:139], v[210:213], v[8:11]
	s_add_u32 s34, s34, 0x200000
	v_mfma_i32_16x16x64_i8 v[60:63], v[132:135], v[190:193], v[60:63]
	v_mfma_i32_16x16x64_i8 v[56:59], v[140:143], v[190:193], v[56:59]
	s_addc_u32 s35, s35, 0
	v_mfma_i32_16x16x64_i8 v[44:47], v[132:135], v[198:201], v[44:47]
	v_mfma_i32_16x16x64_i8 v[40:43], v[140:143], v[198:201], v[40:43]
	v_lshl_add_u64 v[248:249], s[34:35], 0, v[144:145]
	v_mfma_i32_16x16x64_i8 v[28:31], v[132:135], v[206:209], v[28:31]
	v_mfma_i32_16x16x64_i8 v[24:27], v[140:143], v[206:209], v[24:27]
	v_lshl_add_u64 v[224:225], s[34:35], 0, v[148:149]
	v_mfma_i32_16x16x64_i8 v[12:15], v[132:135], v[214:217], v[12:15]
	v_mfma_i32_16x16x64_i8 v[8:11], v[140:143], v[214:217], v[8:11]
	v_mfma_i32_16x16x64_i8 v[52:55], v[162:165], v[186:189], v[52:55]
	v_mfma_i32_16x16x64_i8 v[48:51], v[170:173], v[186:189], v[48:51]
	v_mfma_i32_16x16x64_i8 v[36:39], v[162:165], v[194:197], v[36:39]
	v_mfma_i32_16x16x64_i8 v[32:35], v[170:173], v[194:197], v[32:35]
	v_mfma_i32_16x16x64_i8 v[20:23], v[162:165], v[202:205], v[20:23]
	v_mfma_i32_16x16x64_i8 v[16:19], v[170:173], v[202:205], v[16:19]
	v_mfma_i32_16x16x64_i8 v[4:7], v[162:165], v[210:213], v[4:7]
	v_mfma_i32_16x16x64_i8 v[0:3], v[170:173], v[210:213], v[0:3]
	v_mfma_i32_16x16x64_i8 v[52:55], v[166:169], v[190:193], v[52:55]
	v_mfma_i32_16x16x64_i8 v[48:51], v[174:177], v[190:193], v[48:51]
	v_mfma_i32_16x16x64_i8 v[36:39], v[166:169], v[198:201], v[36:39]
	v_mfma_i32_16x16x64_i8 v[32:35], v[174:177], v[198:201], v[32:35]
	v_mfma_i32_16x16x64_i8 v[20:23], v[166:169], v[206:209], v[20:23]
	v_mfma_i32_16x16x64_i8 v[16:19], v[174:177], v[206:209], v[16:19]
	v_mfma_i32_16x16x64_i8 v[4:7], v[166:169], v[214:217], v[4:7]
	v_mfma_i32_16x16x64_i8 v[0:3], v[174:177], v[214:217], v[0:3]
	s_barrier
	ds_read_b128 v[186:189], v183 offset:32768
	ds_read_b128 v[190:193], v183 offset:33792
	ds_read_b128 v[194:197], v183 offset:34816
	ds_read_b128 v[198:201], v183 offset:35840
	ds_read_b128 v[202:205], v183 offset:36864
	ds_read_b128 v[206:209], v183 offset:37888
	ds_read_b128 v[210:213], v183 offset:38912
	ds_read_b128 v[214:217], v183 offset:39936
	v_add_u32_e32 v140, s54, v181
	v_add_u32_e32 v174, s55, v181
	ds_read_b128 v[124:127], v140
	ds_read_b128 v[132:135], v140 offset:1024
	ds_read_b128 v[136:139], v140 offset:2048
	ds_read_b128 v[140:143], v140 offset:3072
	ds_read_b128 v[162:165], v174
	ds_read_b128 v[166:169], v174 offset:1024
	ds_read_b128 v[170:173], v174 offset:2048
	ds_read_b128 v[174:177], v174 offset:3072
	s_mov_b32 m0, s40
	s_nop 0
	global_load_lds_dwordx4 v[248:249], off
	s_mov_b32 m0, s41
	s_nop 0
	global_load_lds_dwordx4 v[224:225], off
	s_waitcnt vmcnt(8)
	s_waitcnt lgkmcnt(0)
	s_barrier
	s_waitcnt lgkmcnt(0)
	v_mfma_i32_16x16x64_i8 v[116:119], v[124:127], v[186:189], v[116:119]
	v_mfma_i32_16x16x64_i8 v[104:107], v[136:139], v[186:189], v[104:107]
	v_mfma_i32_16x16x64_i8 v[112:115], v[124:127], v[194:197], v[112:115]
	v_mfma_i32_16x16x64_i8 v[108:111], v[136:139], v[194:197], v[108:111]
	s_add_i32 s34, s54, s38
	v_mfma_i32_16x16x64_i8 v[92:95], v[124:127], v[202:205], v[92:95]
	v_mfma_i32_16x16x64_i8 v[88:91], v[136:139], v[202:205], v[88:91]
	v_lshl_add_u64 v[248:249], v[178:179], 0, s[10:11]
	v_mfma_i32_16x16x64_i8 v[76:79], v[124:127], v[210:213], v[76:79]
	v_mfma_i32_16x16x64_i8 v[72:75], v[136:139], v[210:213], v[72:75]
	s_add_u32 s30, s30, 0x200080
	v_mfma_i32_16x16x64_i8 v[116:119], v[132:135], v[190:193], v[116:119]
	v_mfma_i32_16x16x64_i8 v[104:107], v[140:143], v[190:193], v[104:107]
	v_lshl_add_u64 v[250:251], v[218:219], 0, s[10:11]
	v_mfma_i32_16x16x64_i8 v[112:115], v[132:135], v[198:201], v[112:115]
	v_mfma_i32_16x16x64_i8 v[108:111], v[140:143], v[198:201], v[108:111]
	s_addc_u32 s31, s31, 0
	v_mfma_i32_16x16x64_i8 v[92:95], v[132:135], v[206:209], v[92:95]
	v_mfma_i32_16x16x64_i8 v[88:91], v[140:143], v[206:209], v[88:91]
	v_lshl_add_u64 v[252:253], s[30:31], 0, v[146:147]
	v_mfma_i32_16x16x64_i8 v[76:79], v[132:135], v[214:217], v[76:79]
	v_mfma_i32_16x16x64_i8 v[72:75], v[140:143], v[214:217], v[72:75]
	v_lshl_add_u64 v[244:245], s[30:31], 0, v[150:151]
	v_mfma_i32_16x16x64_i8 v[128:131], v[162:165], v[186:189], v[128:131]
	v_mfma_i32_16x16x64_i8 v[120:123], v[170:173], v[186:189], v[120:123]
	v_lshl_add_u64 v[246:247], v[220:221], 0, s[10:11]
	v_mfma_i32_16x16x64_i8 v[100:103], v[162:165], v[194:197], v[100:103]
	v_mfma_i32_16x16x64_i8 v[96:99], v[170:173], v[194:197], v[96:99]
	v_lshl_add_u64 v[178:179], v[222:223], 0, s[10:11]
	v_mfma_i32_16x16x64_i8 v[84:87], v[162:165], v[202:205], v[84:87]
	v_mfma_i32_16x16x64_i8 v[80:83], v[170:173], v[202:205], v[80:83]
	v_mfma_i32_16x16x64_i8 v[68:71], v[162:165], v[210:213], v[68:71]
	v_mfma_i32_16x16x64_i8 v[64:67], v[170:173], v[210:213], v[64:67]
	v_mfma_i32_16x16x64_i8 v[128:131], v[166:169], v[190:193], v[128:131]
	v_mfma_i32_16x16x64_i8 v[120:123], v[174:177], v[190:193], v[120:123]
	v_mfma_i32_16x16x64_i8 v[100:103], v[166:169], v[198:201], v[100:103]
	v_mfma_i32_16x16x64_i8 v[96:99], v[174:177], v[198:201], v[96:99]
	v_mfma_i32_16x16x64_i8 v[84:87], v[166:169], v[206:209], v[84:87]
	v_mfma_i32_16x16x64_i8 v[80:83], v[174:177], v[206:209], v[80:83]
	v_mfma_i32_16x16x64_i8 v[68:71], v[166:169], v[214:217], v[68:71]
	v_mfma_i32_16x16x64_i8 v[64:67], v[174:177], v[214:217], v[64:67]
	s_barrier
	ds_read_b128 v[186:189], v183 offset:49152
	ds_read_b128 v[190:193], v183 offset:50176
	ds_read_b128 v[194:197], v183 offset:51200
	ds_read_b128 v[198:201], v183 offset:52224
	ds_read_b128 v[202:205], v183 offset:53248
	ds_read_b128 v[206:209], v183 offset:54272
	ds_read_b128 v[210:213], v183 offset:55296
	ds_read_b128 v[214:217], v183 offset:56320
	s_mov_b32 m0, s34
	s_nop 0
	global_load_lds_dwordx4 v[248:249], off
	s_add_i32 m0, s34, 0x2000
	s_add_i32 s34, s55, s38
	global_load_lds_dwordx4 v[250:251], off
	s_mov_b32 m0, s34
	s_nop 0
	global_load_lds_dwordx4 v[252:253], off
	s_add_i32 m0, s34, 0x2000
	s_nop 0
	global_load_lds_dwordx4 v[244:245], off
	s_mov_b32 m0, s43
	s_nop 0
	global_load_lds_dwordx4 v[246:247], off
	s_mov_b32 m0, s44
	s_nop 0
	global_load_lds_dwordx4 v[178:179], off
	s_waitcnt vmcnt(8)
	s_waitcnt lgkmcnt(0)
	s_barrier
	s_waitcnt lgkmcnt(0)
	v_mfma_i32_16x16x64_i8 v[60:63], v[124:127], v[186:189], v[60:63]
	v_mfma_i32_16x16x64_i8 v[56:59], v[136:139], v[186:189], v[56:59]
	v_mfma_i32_16x16x64_i8 v[44:47], v[124:127], v[194:197], v[44:47]
	v_mfma_i32_16x16x64_i8 v[40:43], v[136:139], v[194:197], v[40:43]
	v_mfma_i32_16x16x64_i8 v[28:31], v[124:127], v[202:205], v[28:31]
	v_mfma_i32_16x16x64_i8 v[24:27], v[136:139], v[202:205], v[24:27]
	v_mfma_i32_16x16x64_i8 v[12:15], v[124:127], v[210:213], v[12:15]
	v_mfma_i32_16x16x64_i8 v[8:11], v[136:139], v[210:213], v[8:11]
	v_mfma_i32_16x16x64_i8 v[60:63], v[132:135], v[190:193], v[60:63]
	v_mfma_i32_16x16x64_i8 v[56:59], v[140:143], v[190:193], v[56:59]
	v_mfma_i32_16x16x64_i8 v[44:47], v[132:135], v[198:201], v[44:47]
	v_mfma_i32_16x16x64_i8 v[40:43], v[140:143], v[198:201], v[40:43]
	v_mfma_i32_16x16x64_i8 v[28:31], v[132:135], v[206:209], v[28:31]
	v_mfma_i32_16x16x64_i8 v[24:27], v[140:143], v[206:209], v[24:27]
	v_mfma_i32_16x16x64_i8 v[12:15], v[132:135], v[214:217], v[12:15]
	v_mfma_i32_16x16x64_i8 v[8:11], v[140:143], v[214:217], v[8:11]
	v_mfma_i32_16x16x64_i8 v[52:55], v[162:165], v[186:189], v[52:55]
	v_mfma_i32_16x16x64_i8 v[48:51], v[170:173], v[186:189], v[48:51]
	v_mfma_i32_16x16x64_i8 v[36:39], v[162:165], v[194:197], v[36:39]
	v_mfma_i32_16x16x64_i8 v[32:35], v[170:173], v[194:197], v[32:35]
	v_mfma_i32_16x16x64_i8 v[20:23], v[162:165], v[202:205], v[20:23]
	v_mfma_i32_16x16x64_i8 v[16:19], v[170:173], v[202:205], v[16:19]
	v_mfma_i32_16x16x64_i8 v[4:7], v[162:165], v[210:213], v[4:7]
	v_mfma_i32_16x16x64_i8 v[0:3], v[170:173], v[210:213], v[0:3]
	v_mfma_i32_16x16x64_i8 v[52:55], v[166:169], v[190:193], v[52:55]
	v_mfma_i32_16x16x64_i8 v[48:51], v[174:177], v[190:193], v[48:51]
	v_mfma_i32_16x16x64_i8 v[36:39], v[166:169], v[198:201], v[36:39]
	v_mfma_i32_16x16x64_i8 v[32:35], v[174:177], v[198:201], v[32:35]
	v_mfma_i32_16x16x64_i8 v[20:23], v[166:169], v[206:209], v[20:23]
	v_mfma_i32_16x16x64_i8 v[16:19], v[174:177], v[206:209], v[16:19]
	v_mfma_i32_16x16x64_i8 v[4:7], v[166:169], v[214:217], v[4:7]
	v_mfma_i32_16x16x64_i8 v[0:3], v[174:177], v[214:217], v[0:3]
	s_barrier
	s_add_i32 s53, s53, 2
	s_add_u32 s51, s51, 0x100
	s_addc_u32 s52, s52, 0
	s_add_u32 s28, s28, 0x100
	s_addc_u32 s29, s29, 0
	s_cmpk_gt_u32 s53, 0x7d
	s_cbranch_scc0 .LBB0_1841
	s_setprio 0
	s_and_b64 vcc, exec, s[12:13]
	s_cbranch_vccz .LBB0_1844
	s_barrier
